# more asm-adjacent padding nops removed in EpiUp
# speedup vs baseline: 1.0091x; 1.0011x over previous
; #define PG8_LAS __attribute__((address_space(3)))
; __device__ __forceinline__ float dpp_ror1(float x) { float r; asm volatile("s_nop 1\n\tv_mov_b32_dpp %0, %1 row_ror:1 row_mask:0xf bank_mask:0xf" : "=&v"(r) : "v"(x)); return r; }
; __device__ __forceinline__ float dpp_ror2(float x) { float r; asm volatile("s_nop 1\n\tv_mov_b32_dpp %0, %1 row_ror:2 row_mask:0xf bank_mask:0xf" : "=&v"(r) : "v"(x)); return r; }
;     __device__ __forceinline__ void operator()(f32x4 (&acc)[2][2][4][2], const Unit& u, int wr, int wc, int fr_, int fq_) const {
;     ...
;                 for (int n = 0; n < 2; ++n) {
;                     const int ct = bj * HALF + wc * 32 + 8 * fq + 4 * n;
;                     const int cidx = bj * 5632 + jcol + 4 * n;
;                     const f32x4 w0 = *(const f32x4*)(cw + cidx), w1 = *(const f32x4*)(cw + 11264 + cidx), w2 = *(const f32x4*)(cw + 22528 + cidx), b4 = *(const f32x4*)(cb + cidx);
;                     f32x4 pR1 = (f32x4){0.f, 0.f, 0.f, 0.f}, pR2 = pR1;
;                     if (blk) { const f32x4 h14 = *(const PG8_LAS f32x4*)(hal + ((blk - 1) * 2 + 0) * 256 + ct) * rs14, h15 = *(const PG8_LAS f32x4*)(hal + ((blk - 1) * 2 + 1) * 256 + ct) * rs15;
;                         pR1 = h15; pR2 = (fr == 0) ? h14 : h15; }
; #pragma unroll
;                     for (int m = 0; m < 4; ++m) {
;                         const f32x4 U = acc[ai][bj][m][n] * rsr[m];
;                         f32x4 R1, R2;
; #pragma unroll
;                         for (int i = 0; i < 4; ++i) { R1[i] = dpp_ror1(U[i]); R2[i] = dpp_ror2(U[i]); }
;                         const f32x4 U1 = (fr >= 1) ? R1 : pR1, U2 = (fr >= 2) ? R2 : pR2;
;                         const f32x4 C = b4 + w0 * U2 + w1 * U1 + w2 * U;
;                         acc[ai][bj][m][n] = C; pR1 = R1; pR2 = R2;
.LBB0_1718:
	v_cmp_lt_i32_e64 s[8:9], 1, v178
	v_pk_mul_f32 v[126:127], v[126:127], v[192:193] op_sel_hi:[1,0]
	v_pk_mul_f32 v[124:125], v[124:125], v[192:193] op_sel_hi:[1,0]
	v_cmp_lt_i32_e64 s[6:7], 0, v178
	s_nop 1
	v_mov_b32_dpp v199, v124 row_ror:1 row_mask:0xf bank_mask:0xf
	v_mov_b32_dpp v204, v124 row_ror:2 row_mask:0xf bank_mask:0xf
	v_mov_b32_dpp v205, v125 row_ror:1 row_mask:0xf bank_mask:0xf
	v_mov_b32_dpp v206, v125 row_ror:2 row_mask:0xf bank_mask:0xf
	v_mov_b32_dpp v207, v126 row_ror:1 row_mask:0xf bank_mask:0xf
	v_mov_b32_dpp v208, v126 row_ror:2 row_mask:0xf bank_mask:0xf
	v_mov_b32_dpp v209, v127 row_ror:1 row_mask:0xf bank_mask:0xf
	v_mov_b32_dpp v210, v127 row_ror:2 row_mask:0xf bank_mask:0xf
	v_cndmask_b32_e64 v202, v187, v204, s[8:9]
	v_cndmask_b32_e64 v200, v189, v208, s[8:9]
	v_cndmask_b32_e64 v201, v193, v210, s[8:9]
	v_cndmask_b32_e64 v203, v191, v206, s[8:9]
	v_cndmask_b32_e64 v174, v174, v199, s[6:7]
	v_cndmask_b32_e64 v175, v175, v205, s[6:7]
	v_cndmask_b32_e64 v172, v172, v207, s[6:7]
	v_cndmask_b32_e64 v173, v173, v209, s[6:7]
	s_waitcnt vmcnt(0)
	v_pk_fma_f32 v[202:203], v[136:137], v[202:203], v[140:141]
	v_pk_fma_f32 v[200:201], v[138:139], v[200:201], v[142:143]
	v_pk_fma_f32 v[174:175], v[128:129], v[174:175], v[202:203]
	v_pk_fma_f32 v[172:173], v[130:131], v[172:173], v[200:201]
	v_pk_fma_f32 v[124:125], v[124:125], v[132:133], v[174:175]
	v_pk_fma_f32 v[126:127], v[126:127], v[134:135], v[172:173]
	v_pk_mul_f32 v[122:123], v[122:123], v[190:191] op_sel_hi:[1,0]
	v_pk_mul_f32 v[120:121], v[120:121], v[190:191] op_sel_hi:[1,0]
	s_nop 1
	v_mov_b32_dpp v187, v120 row_ror:1 row_mask:0xf bank_mask:0xf
	v_mov_b32_dpp v189, v120 row_ror:2 row_mask:0xf bank_mask:0xf
	v_mov_b32_dpp v191, v121 row_ror:1 row_mask:0xf bank_mask:0xf
	v_mov_b32_dpp v193, v121 row_ror:2 row_mask:0xf bank_mask:0xf
	v_mov_b32_dpp v211, v122 row_ror:1 row_mask:0xf bank_mask:0xf
	v_mov_b32_dpp v212, v122 row_ror:2 row_mask:0xf bank_mask:0xf
	v_mov_b32_dpp v213, v123 row_ror:1 row_mask:0xf bank_mask:0xf
	v_mov_b32_dpp v214, v123 row_ror:2 row_mask:0xf bank_mask:0xf
	v_cndmask_b32_e64 v202, v204, v189, s[8:9]
	v_cndmask_b32_e64 v200, v208, v212, s[8:9]
	v_cndmask_b32_e64 v201, v210, v214, s[8:9]
	v_cndmask_b32_e64 v203, v206, v193, s[8:9]
	v_cndmask_b32_e64 v172, v199, v187, s[6:7]
	v_cndmask_b32_e64 v173, v205, v191, s[6:7]
	v_cndmask_b32_e64 v174, v207, v211, s[6:7]
	v_cndmask_b32_e64 v175, v209, v213, s[6:7]
	v_pk_fma_f32 v[202:203], v[136:137], v[202:203], v[140:141]
	v_pk_fma_f32 v[200:201], v[138:139], v[200:201], v[142:143]
	v_pk_fma_f32 v[172:173], v[128:129], v[172:173], v[202:203]
	v_pk_fma_f32 v[174:175], v[130:131], v[174:175], v[200:201]
	v_pk_fma_f32 v[120:121], v[120:121], v[132:133], v[172:173]
	v_pk_fma_f32 v[122:123], v[122:123], v[134:135], v[174:175]
	v_pk_mul_f32 v[106:107], v[106:107], v[188:189] op_sel_hi:[1,0]
	v_pk_mul_f32 v[104:105], v[104:105], v[188:189] op_sel_hi:[1,0]
	s_nop 1
	v_mov_b32_dpp v199, v104 row_ror:1 row_mask:0xf bank_mask:0xf
	v_mov_b32_dpp v204, v104 row_ror:2 row_mask:0xf bank_mask:0xf
	v_mov_b32_dpp v205, v105 row_ror:1 row_mask:0xf bank_mask:0xf
	v_mov_b32_dpp v206, v105 row_ror:2 row_mask:0xf bank_mask:0xf
	v_mov_b32_dpp v207, v106 row_ror:1 row_mask:0xf bank_mask:0xf
	v_mov_b32_dpp v208, v106 row_ror:2 row_mask:0xf bank_mask:0xf
	v_mov_b32_dpp v209, v107 row_ror:1 row_mask:0xf bank_mask:0xf
	v_mov_b32_dpp v210, v107 row_ror:2 row_mask:0xf bank_mask:0xf
	v_cndmask_b32_e64 v202, v189, v204, s[8:9]
	v_cndmask_b32_e64 v200, v212, v208, s[8:9]
	v_cndmask_b32_e64 v201, v214, v210, s[8:9]
	v_cndmask_b32_e64 v203, v193, v206, s[8:9]
	v_cndmask_b32_e64 v172, v187, v199, s[6:7]
	v_cndmask_b32_e64 v173, v191, v205, s[6:7]
	v_cndmask_b32_e64 v174, v211, v207, s[6:7]
	v_cndmask_b32_e64 v175, v213, v209, s[6:7]
	v_pk_fma_f32 v[202:203], v[136:137], v[202:203], v[140:141]
	v_pk_fma_f32 v[200:201], v[138:139], v[200:201], v[142:143]
	v_pk_fma_f32 v[172:173], v[128:129], v[172:173], v[202:203]
	v_pk_fma_f32 v[174:175], v[130:131], v[174:175], v[200:201]
	v_pk_fma_f32 v[104:105], v[104:105], v[132:133], v[172:173]
	v_pk_fma_f32 v[106:107], v[106:107], v[134:135], v[174:175]
	v_pk_mul_f32 v[82:83], v[82:83], v[186:187] op_sel_hi:[1,0]
	v_pk_mul_f32 v[80:81], v[80:81], v[186:187] op_sel_hi:[1,0]
	s_nop 1
	v_mov_b32_dpp v172, v80 row_ror:1 row_mask:0xf bank_mask:0xf
	v_mov_b32_dpp v187, v80 row_ror:2 row_mask:0xf bank_mask:0xf
	v_mov_b32_dpp v173, v81 row_ror:1 row_mask:0xf bank_mask:0xf
	v_mov_b32_dpp v189, v81 row_ror:2 row_mask:0xf bank_mask:0xf
	v_mov_b32_dpp v174, v82 row_ror:1 row_mask:0xf bank_mask:0xf
	v_mov_b32_dpp v191, v82 row_ror:2 row_mask:0xf bank_mask:0xf
	v_mov_b32_dpp v175, v83 row_ror:1 row_mask:0xf bank_mask:0xf
	v_mov_b32_dpp v193, v83 row_ror:2 row_mask:0xf bank_mask:0xf
	v_cndmask_b32_e64 v202, v204, v187, s[8:9]
	v_cndmask_b32_e64 v200, v208, v191, s[8:9]
	v_cndmask_b32_e64 v201, v210, v193, s[8:9]
	v_cndmask_b32_e64 v203, v206, v189, s[8:9]
	v_cndmask_b32_e64 v172, v199, v172, s[6:7]
	v_cndmask_b32_e64 v173, v205, v173, s[6:7]
	v_cndmask_b32_e64 v174, v207, v174, s[6:7]
	v_cndmask_b32_e64 v175, v209, v175, s[6:7]
	v_pk_fma_f32 v[136:137], v[136:137], v[202:203], v[140:141]
	v_pk_fma_f32 v[138:139], v[138:139], v[200:201], v[142:143]
	v_pk_fma_f32 v[128:129], v[128:129], v[172:173], v[136:137]
	v_pk_fma_f32 v[130:131], v[130:131], v[174:175], v[138:139]
	v_pk_fma_f32 v[80:81], v[80:81], v[132:133], v[128:129]
	v_pk_fma_f32 v[82:83], v[82:83], v[134:135], v[130:131]
	s_nop 0
	v_or_b32_e32 v128, 4, v180
	v_ashrrev_i32_e32 v129, 31, v128
	v_lshlrev_b64 v[128:129], 2, v[128:129]
	v_lshl_add_u64 v[172:173], s[42:43], 0, v[128:129]
	global_load_dwordx4 v[136:139], v[164:165], off offset:16
	v_lshl_add_u64 v[174:175], s[44:45], 0, v[128:129]
	global_load_dwordx4 v[132:135], v[172:173], off
	global_load_dwordx4 v[128:131], v[174:175], off
	global_load_dwordx4 v[140:143], v[166:167], off offset:16
	s_and_b64 vcc, exec, s[12:13]
	v_mov_b32_e32 v199, 0
	v_mov_b32_e32 v202, 0
	v_mov_b32_e32 v203, 0
	v_mov_b32_e32 v204, 0
	v_mov_b32_e32 v206, 0
	v_mov_b32_e32 v205, 0
	v_mov_b32_e32 v207, 0
	s_cbranch_vccnz .LBB0_1720
	ds_read_b128 v[198:201], v226 offset:16
	ds_read_b128 v[204:207], v179 offset:16
	v_mov_b32_e32 v202, v196
	v_mov_b32_e32 v203, v196
	s_waitcnt lgkmcnt(1)
	v_pk_mul_f32 v[208:209], v[196:197], v[198:199]
	v_mov_b32_e32 v198, v194
	v_mov_b32_e32 v199, v194
	v_pk_mul_f32 v[200:201], v[202:203], v[200:201]
	s_waitcnt lgkmcnt(0)
	v_pk_mul_f32 v[202:203], v[198:199], v[206:207]
	v_pk_mul_f32 v[198:199], v[194:195], v[204:205]
	v_cndmask_b32_e64 v205, v202, v200, s[10:11]
	v_cndmask_b32_e64 v207, v203, v201, s[10:11]
	v_cndmask_b32_e64 v204, v198, v208, s[10:11]
	v_cndmask_b32_e64 v206, v199, v209, s[10:11]
; #define PG8_LAS __attribute__((address_space(3)))
; __device__ __forceinline__ float dpp_ror1(float x) { float r; asm volatile("s_nop 1\n\tv_mov_b32_dpp %0, %1 row_ror:1 row_mask:0xf bank_mask:0xf" : "=&v"(r) : "v"(x)); return r; }
; __device__ __forceinline__ float dpp_ror2(float x) { float r; asm volatile("s_nop 1\n\tv_mov_b32_dpp %0, %1 row_ror:2 row_mask:0xf bank_mask:0xf" : "=&v"(r) : "v"(x)); return r; }
;     __device__ __forceinline__ void operator()(f32x4 (&acc)[2][2][4][2], const Unit& u, int wr, int wc, int fr_, int fq_) const {
;     ...
;                 for (int n = 0; n < 2; ++n) {
;                     const int ct = bj * HALF + wc * 32 + 8 * fq + 4 * n;
;                     const int cidx = bj * 5632 + jcol + 4 * n;
;                     const f32x4 w0 = *(const f32x4*)(cw + cidx), w1 = *(const f32x4*)(cw + 11264 + cidx), w2 = *(const f32x4*)(cw + 22528 + cidx), b4 = *(const f32x4*)(cb + cidx);
;                     f32x4 pR1 = (f32x4){0.f, 0.f, 0.f, 0.f}, pR2 = pR1;
;                     if (blk) { const f32x4 h14 = *(const PG8_LAS f32x4*)(hal + ((blk - 1) * 2 + 0) * 256 + ct) * rs14, h15 = *(const PG8_LAS f32x4*)(hal + ((blk - 1) * 2 + 1) * 256 + ct) * rs15;
;                         pR1 = h15; pR2 = (fr == 0) ? h14 : h15; }
; #pragma unroll
;                     for (int m = 0; m < 4; ++m) {
;                         const f32x4 U = acc[ai][bj][m][n] * rsr[m];
;                         f32x4 R1, R2;
; #pragma unroll
;                         for (int i = 0; i < 4; ++i) { R1[i] = dpp_ror1(U[i]); R2[i] = dpp_ror2(U[i]); }
;                         const f32x4 U1 = (fr >= 1) ? R1 : pR1, U2 = (fr >= 2) ? R2 : pR2;
;                         const f32x4 C = b4 + w0 * U2 + w1 * U1 + w2 * U;
;                         acc[ai][bj][m][n] = C; pR1 = R1; pR2 = R2;
;                         asm volatile("" : "+v"(acc[ai][bj][m][n]));
;                         __builtin_amdgcn_sched_barrier(0);
;                     }
.LBB0_1720:
	v_mov_b32_e32 v193, v192
	v_mov_b32_e32 v200, v192
	v_mov_b32_e32 v201, v192
	v_pk_mul_f32 v[118:119], v[118:119], v[200:201]
	v_pk_mul_f32 v[116:117], v[116:117], v[192:193]
	v_mov_b32_e32 v187, v186
	s_nop 1
	v_mov_b32_dpp v210, v116 row_ror:1 row_mask:0xf bank_mask:0xf
	v_mov_b32_dpp v211, v116 row_ror:2 row_mask:0xf bank_mask:0xf
	v_mov_b32_dpp v212, v117 row_ror:1 row_mask:0xf bank_mask:0xf
	v_mov_b32_dpp v213, v117 row_ror:2 row_mask:0xf bank_mask:0xf
	v_mov_b32_dpp v214, v118 row_ror:1 row_mask:0xf bank_mask:0xf
	v_mov_b32_dpp v215, v118 row_ror:2 row_mask:0xf bank_mask:0xf
	v_mov_b32_dpp v227, v119 row_ror:1 row_mask:0xf bank_mask:0xf
	v_mov_b32_dpp v228, v119 row_ror:2 row_mask:0xf bank_mask:0xf
	v_cndmask_b32_e64 v204, v204, v211, s[8:9]
	v_cndmask_b32_e64 v208, v205, v215, s[8:9]
	v_cndmask_b32_e64 v209, v207, v228, s[8:9]
	v_cndmask_b32_e64 v205, v206, v213, s[8:9]
	v_cndmask_b32_e64 v202, v202, v214, s[6:7]
	v_cndmask_b32_e64 v203, v203, v227, s[6:7]
	v_cndmask_b32_e64 v198, v198, v210, s[6:7]
	v_cndmask_b32_e64 v199, v199, v212, s[6:7]
	s_waitcnt vmcnt(0)
	v_pk_fma_f32 v[206:207], v[138:139], v[208:209], v[142:143]
	v_pk_fma_f32 v[204:205], v[136:137], v[204:205], v[140:141]
	v_pk_fma_f32 v[202:203], v[134:135], v[202:203], v[206:207]
	v_pk_fma_f32 v[198:199], v[132:133], v[198:199], v[204:205]
	v_mov_b32_e32 v191, v190
	v_mov_b32_e32 v189, v188
	v_pk_fma_f32 v[118:119], v[118:119], v[130:131], v[202:203]
	v_pk_fma_f32 v[116:117], v[116:117], v[128:129], v[198:199]
	v_mov_b32_e32 v202, v190
	v_mov_b32_e32 v203, v190
	v_pk_mul_f32 v[114:115], v[114:115], v[202:203]
	v_pk_mul_f32 v[112:113], v[112:113], v[190:191]
	s_nop 1
	v_mov_b32_dpp v229, v112 row_ror:1 row_mask:0xf bank_mask:0xf
	v_mov_b32_dpp v230, v112 row_ror:2 row_mask:0xf bank_mask:0xf
	v_mov_b32_dpp v231, v113 row_ror:1 row_mask:0xf bank_mask:0xf
	v_mov_b32_dpp v232, v113 row_ror:2 row_mask:0xf bank_mask:0xf
	v_mov_b32_dpp v233, v114 row_ror:1 row_mask:0xf bank_mask:0xf
	v_mov_b32_dpp v234, v114 row_ror:2 row_mask:0xf bank_mask:0xf
	v_mov_b32_dpp v235, v115 row_ror:1 row_mask:0xf bank_mask:0xf
	v_mov_b32_dpp v236, v115 row_ror:2 row_mask:0xf bank_mask:0xf
	v_cndmask_b32_e64 v208, v211, v230, s[8:9]
	v_cndmask_b32_e64 v206, v215, v234, s[8:9]
	v_cndmask_b32_e64 v207, v228, v236, s[8:9]
	v_cndmask_b32_e64 v209, v213, v232, s[8:9]
	v_cndmask_b32_e64 v198, v214, v233, s[6:7]
	v_cndmask_b32_e64 v199, v227, v235, s[6:7]
	v_cndmask_b32_e64 v204, v210, v229, s[6:7]
	v_cndmask_b32_e64 v205, v212, v231, s[6:7]
	v_pk_fma_f32 v[206:207], v[138:139], v[206:207], v[142:143]
	v_pk_fma_f32 v[208:209], v[136:137], v[208:209], v[140:141]
	v_pk_fma_f32 v[198:199], v[134:135], v[198:199], v[206:207]
	v_pk_fma_f32 v[204:205], v[132:133], v[204:205], v[208:209]
	v_pk_fma_f32 v[114:115], v[114:115], v[130:131], v[198:199]
	v_pk_fma_f32 v[112:113], v[112:113], v[128:129], v[204:205]
	v_mov_b32_e32 v204, v188
	v_mov_b32_e32 v205, v188
	v_pk_mul_f32 v[110:111], v[110:111], v[204:205]
	v_pk_mul_f32 v[108:109], v[108:109], v[188:189]
	s_nop 1
	v_mov_b32_dpp v212, v108 row_ror:1 row_mask:0xf bank_mask:0xf
	v_mov_b32_dpp v213, v108 row_ror:2 row_mask:0xf bank_mask:0xf
	v_mov_b32_dpp v214, v109 row_ror:1 row_mask:0xf bank_mask:0xf
	v_mov_b32_dpp v215, v109 row_ror:2 row_mask:0xf bank_mask:0xf
	v_mov_b32_dpp v227, v110 row_ror:1 row_mask:0xf bank_mask:0xf
	v_mov_b32_dpp v228, v110 row_ror:2 row_mask:0xf bank_mask:0xf
	v_mov_b32_dpp v237, v111 row_ror:1 row_mask:0xf bank_mask:0xf
	v_mov_b32_dpp v238, v111 row_ror:2 row_mask:0xf bank_mask:0xf
	v_cndmask_b32_e64 v210, v230, v213, s[8:9]
	v_cndmask_b32_e64 v208, v234, v228, s[8:9]
	v_cndmask_b32_e64 v209, v236, v238, s[8:9]
	v_cndmask_b32_e64 v211, v232, v215, s[8:9]
	v_cndmask_b32_e64 v198, v233, v227, s[6:7]
	v_cndmask_b32_e64 v199, v235, v237, s[6:7]
	v_cndmask_b32_e64 v206, v229, v212, s[6:7]
	v_cndmask_b32_e64 v207, v231, v214, s[6:7]
	v_pk_fma_f32 v[208:209], v[138:139], v[208:209], v[142:143]
	v_pk_fma_f32 v[210:211], v[136:137], v[210:211], v[140:141]
	v_pk_fma_f32 v[198:199], v[134:135], v[198:199], v[208:209]
	v_pk_fma_f32 v[206:207], v[132:133], v[206:207], v[210:211]
	v_pk_fma_f32 v[110:111], v[110:111], v[130:131], v[198:199]
	v_pk_fma_f32 v[108:109], v[108:109], v[128:129], v[206:207]
	v_mov_b32_e32 v206, v186
	v_mov_b32_e32 v207, v186
	v_pk_mul_f32 v[94:95], v[94:95], v[206:207]
	v_pk_mul_f32 v[92:93], v[92:93], v[186:187]
	s_nop 1
	v_mov_b32_dpp v208, v92 row_ror:1 row_mask:0xf bank_mask:0xf
	v_mov_b32_dpp v229, v92 row_ror:2 row_mask:0xf bank_mask:0xf
	v_mov_b32_dpp v209, v93 row_ror:1 row_mask:0xf bank_mask:0xf
	v_mov_b32_dpp v230, v93 row_ror:2 row_mask:0xf bank_mask:0xf
	v_mov_b32_dpp v198, v94 row_ror:1 row_mask:0xf bank_mask:0xf
	v_mov_b32_dpp v210, v94 row_ror:2 row_mask:0xf bank_mask:0xf
	v_mov_b32_dpp v199, v95 row_ror:1 row_mask:0xf bank_mask:0xf
	v_mov_b32_dpp v211, v95 row_ror:2 row_mask:0xf bank_mask:0xf
	v_cndmask_b32_e64 v208, v212, v208, s[6:7]
	v_cndmask_b32_e64 v210, v228, v210, s[8:9]
	v_cndmask_b32_e64 v211, v238, v211, s[8:9]
	v_cndmask_b32_e64 v212, v213, v229, s[8:9]
	v_cndmask_b32_e64 v213, v215, v230, s[8:9]
	v_cndmask_b32_e64 v198, v227, v198, s[6:7]
	v_cndmask_b32_e64 v199, v237, v199, s[6:7]
	v_cndmask_b32_e64 v209, v214, v209, s[6:7]
	v_pk_fma_f32 v[138:139], v[138:139], v[210:211], v[142:143]
	v_pk_fma_f32 v[136:137], v[136:137], v[212:213], v[140:141]
	v_pk_fma_f32 v[134:135], v[134:135], v[198:199], v[138:139]
	v_pk_fma_f32 v[132:133], v[132:133], v[208:209], v[136:137]
	v_pk_fma_f32 v[94:95], v[94:95], v[130:131], v[134:135]
	v_pk_fma_f32 v[92:93], v[92:93], v[128:129], v[132:133]
	s_nop 0
	s_movk_i32 s0, 0x5000
	v_add_co_u32_e32 v208, vcc, s0, v164
	v_mov_b32_e32 v198, 0
	s_nop 0
	v_addc_co_u32_e32 v209, vcc, 0, v165, vcc
	v_add_co_u32_e32 v210, vcc, s0, v168
	v_mov_b32_e32 v212, 0
	s_nop 0
	v_addc_co_u32_e32 v211, vcc, 0, v169, vcc
	v_add_co_u32_e32 v136, vcc, 0x5000, v170
	global_load_dwordx4 v[132:135], v[208:209], off offset:2048
	global_load_dwordx4 v[128:131], v[210:211], off offset:2048
	v_addc_co_u32_e32 v137, vcc, 0, v171, vcc
	v_add_co_u32_e32 v140, vcc, 0x5000, v166
	global_load_dwordx4 v[136:139], v[136:137], off offset:2048
	s_nop 0
	v_addc_co_u32_e32 v141, vcc, 0, v167, vcc
	global_load_dwordx4 v[140:143], v[140:141], off offset:2048
	s_and_b64 vcc, exec, s[12:13]
	v_mov_b32_e32 v213, 0
	v_mov_b32_e32 v214, 0
	v_mov_b32_e32 v215, 0
	v_mov_b32_e32 v199, 0
	v_mov_b32_e32 v228, 0
	v_mov_b32_e32 v227, 0
	v_mov_b32_e32 v229, 0
	s_cbranch_vccnz .LBB0_1722
; #define PG8_LAS __attribute__((address_space(3)))
;     __device__ __forceinline__ void operator()(f32x4 (&acc)[2][2][4][2], const Unit& u, int wr, int wc, int fr_, int fq_) const {
;     ...
;                     if (blk) { const f32x4 h14 = *(const PG8_LAS f32x4*)(hal + ((blk - 1) * 2 + 0) * 256 + ct) * rs14, h15 = *(const PG8_LAS f32x4*)(hal + ((blk - 1) * 2 + 1) * 256 + ct) * rs15;
;                         pR1 = h15; pR2 = (fr == 0) ? h14 : h15; }
	ds_read_b128 v[212:215], v226 offset:512
	ds_read_b128 v[228:231], v179 offset:512
	v_mov_b32_e32 v232, v196
	v_mov_b32_e32 v233, v196
	s_waitcnt lgkmcnt(1)
	v_pk_mul_f32 v[234:235], v[196:197], v[212:213]
	v_mov_b32_e32 v212, v194
	v_mov_b32_e32 v213, v194
	v_pk_mul_f32 v[232:233], v[232:233], v[214:215]
	s_waitcnt lgkmcnt(0)
	v_pk_mul_f32 v[214:215], v[212:213], v[230:231]
	v_pk_mul_f32 v[212:213], v[194:195], v[228:229]
	v_cndmask_b32_e64 v227, v214, v232, s[10:11]
	v_cndmask_b32_e64 v229, v215, v233, s[10:11]
	v_cndmask_b32_e64 v199, v212, v234, s[10:11]
	v_cndmask_b32_e64 v228, v213, v235, s[10:11]
; #define PG8_LAS __attribute__((address_space(3)))
; __device__ __forceinline__ float dpp_ror1(float x) { float r; asm volatile("s_nop 1\n\tv_mov_b32_dpp %0, %1 row_ror:1 row_mask:0xf bank_mask:0xf" : "=&v"(r) : "v"(x)); return r; }
; __device__ __forceinline__ float dpp_ror2(float x) { float r; asm volatile("s_nop 1\n\tv_mov_b32_dpp %0, %1 row_ror:2 row_mask:0xf bank_mask:0xf" : "=&v"(r) : "v"(x)); return r; }
;     __device__ __forceinline__ void operator()(f32x4 (&acc)[2][2][4][2], const Unit& u, int wr, int wc, int fr_, int fq_) const {
;     ...
;                 for (int n = 0; n < 2; ++n) {
;                     const int ct = bj * HALF + wc * 32 + 8 * fq + 4 * n;
;                     const int cidx = bj * 5632 + jcol + 4 * n;
;                     const f32x4 w0 = *(const f32x4*)(cw + cidx), w1 = *(const f32x4*)(cw + 11264 + cidx), w2 = *(const f32x4*)(cw + 22528 + cidx), b4 = *(const f32x4*)(cb + cidx);
;                     f32x4 pR1 = (f32x4){0.f, 0.f, 0.f, 0.f}, pR2 = pR1;
;                     if (blk) { const f32x4 h14 = *(const PG8_LAS f32x4*)(hal + ((blk - 1) * 2 + 0) * 256 + ct) * rs14, h15 = *(const PG8_LAS f32x4*)(hal + ((blk - 1) * 2 + 1) * 256 + ct) * rs15;
;                         pR1 = h15; pR2 = (fr == 0) ? h14 : h15; }
; #pragma unroll
;                     for (int m = 0; m < 4; ++m) {
;                         const f32x4 U = acc[ai][bj][m][n] * rsr[m];
;                         f32x4 R1, R2;
; #pragma unroll
;                         for (int i = 0; i < 4; ++i) { R1[i] = dpp_ror1(U[i]); R2[i] = dpp_ror2(U[i]); }
;                         const f32x4 U1 = (fr >= 1) ? R1 : pR1, U2 = (fr >= 2) ? R2 : pR2;
;                         const f32x4 C = b4 + w0 * U2 + w1 * U1 + w2 * U;
;                         acc[ai][bj][m][n] = C; pR1 = R1; pR2 = R2;
;                         asm volatile("" : "+v"(acc[ai][bj][m][n]));
;                         __builtin_amdgcn_sched_barrier(0);
;                     }
.LBB0_1722:
	v_pk_mul_f32 v[102:103], v[102:103], v[200:201]
	v_pk_mul_f32 v[100:101], v[100:101], v[192:193]
	v_cmp_gt_i32_e64 s[0:1], 2, v178
	s_nop 1
	v_mov_b32_dpp v232, v100 row_ror:1 row_mask:0xf bank_mask:0xf
	v_mov_b32_dpp v233, v100 row_ror:2 row_mask:0xf bank_mask:0xf
	v_mov_b32_dpp v234, v101 row_ror:1 row_mask:0xf bank_mask:0xf
	v_mov_b32_dpp v235, v101 row_ror:2 row_mask:0xf bank_mask:0xf
	v_mov_b32_dpp v236, v102 row_ror:1 row_mask:0xf bank_mask:0xf
	v_mov_b32_dpp v237, v102 row_ror:2 row_mask:0xf bank_mask:0xf
	v_mov_b32_dpp v238, v103 row_ror:1 row_mask:0xf bank_mask:0xf
	v_mov_b32_dpp v239, v103 row_ror:2 row_mask:0xf bank_mask:0xf
	v_cndmask_b32_e64 v230, v199, v233, s[8:9]
	v_cndmask_b32_e64 v200, v214, v236, s[6:7]
	v_cndmask_b32_e64 v201, v215, v238, s[6:7]
	v_cndmask_b32_e64 v214, v227, v237, s[8:9]
	v_cndmask_b32_e64 v215, v229, v239, s[8:9]
	v_cndmask_b32_e64 v231, v228, v235, s[8:9]
	v_cndmask_b32_e64 v212, v212, v232, s[6:7]
	v_cndmask_b32_e64 v213, v213, v234, s[6:7]
	s_waitcnt vmcnt(0)
	v_pk_fma_f32 v[214:215], v[134:135], v[214:215], v[142:143]
	v_pk_fma_f32 v[228:229], v[132:133], v[230:231], v[140:141]
	v_pk_fma_f32 v[200:201], v[130:131], v[200:201], v[214:215]
	v_pk_fma_f32 v[212:213], v[128:129], v[212:213], v[228:229]
	v_pk_fma_f32 v[102:103], v[102:103], v[138:139], v[200:201]
	v_pk_fma_f32 v[100:101], v[100:101], v[136:137], v[212:213]
	v_pk_mul_f32 v[98:99], v[98:99], v[202:203]
	v_pk_mul_f32 v[96:97], v[96:97], v[190:191]
	s_nop 1
	v_mov_b32_dpp v199, v96 row_ror:1 row_mask:0xf bank_mask:0xf
	v_mov_b32_dpp v227, v96 row_ror:2 row_mask:0xf bank_mask:0xf
	v_mov_b32_dpp v228, v97 row_ror:1 row_mask:0xf bank_mask:0xf
	v_mov_b32_dpp v229, v97 row_ror:2 row_mask:0xf bank_mask:0xf
	v_mov_b32_dpp v230, v98 row_ror:1 row_mask:0xf bank_mask:0xf
	v_mov_b32_dpp v231, v98 row_ror:2 row_mask:0xf bank_mask:0xf
	v_mov_b32_dpp v240, v99 row_ror:1 row_mask:0xf bank_mask:0xf
	v_mov_b32_dpp v241, v99 row_ror:2 row_mask:0xf bank_mask:0xf
	v_cndmask_b32_e64 v214, v233, v227, s[8:9]
	v_cndmask_b32_e64 v212, v237, v231, s[8:9]
	v_cndmask_b32_e64 v213, v239, v241, s[8:9]
	v_cndmask_b32_e64 v215, v235, v229, s[8:9]
	v_cndmask_b32_e64 v200, v236, v230, s[6:7]
	v_cndmask_b32_e64 v201, v238, v240, s[6:7]
	v_cndmask_b32_e64 v202, v232, v199, s[6:7]
	v_cndmask_b32_e64 v203, v234, v228, s[6:7]
	v_pk_fma_f32 v[212:213], v[134:135], v[212:213], v[142:143]
	v_pk_fma_f32 v[214:215], v[132:133], v[214:215], v[140:141]
	v_pk_fma_f32 v[200:201], v[130:131], v[200:201], v[212:213]
	v_pk_fma_f32 v[202:203], v[128:129], v[202:203], v[214:215]
	v_pk_fma_f32 v[98:99], v[98:99], v[138:139], v[200:201]
	v_pk_fma_f32 v[96:97], v[96:97], v[136:137], v[202:203]
	v_pk_mul_f32 v[90:91], v[90:91], v[204:205]
	v_pk_mul_f32 v[88:89], v[88:89], v[188:189]
	s_nop 1
	v_mov_b32_dpp v214, v88 row_ror:1 row_mask:0xf bank_mask:0xf
	v_mov_b32_dpp v215, v88 row_ror:2 row_mask:0xf bank_mask:0xf
	v_mov_b32_dpp v232, v89 row_ror:1 row_mask:0xf bank_mask:0xf
	v_mov_b32_dpp v233, v89 row_ror:2 row_mask:0xf bank_mask:0xf
	v_mov_b32_dpp v234, v90 row_ror:1 row_mask:0xf bank_mask:0xf
	v_mov_b32_dpp v235, v90 row_ror:2 row_mask:0xf bank_mask:0xf
	v_mov_b32_dpp v236, v91 row_ror:1 row_mask:0xf bank_mask:0xf
	v_mov_b32_dpp v237, v91 row_ror:2 row_mask:0xf bank_mask:0xf
	v_cndmask_b32_e64 v212, v227, v215, s[8:9]
	v_cndmask_b32_e64 v204, v231, v235, s[8:9]
	v_cndmask_b32_e64 v205, v241, v237, s[8:9]
	v_cndmask_b32_e64 v213, v229, v233, s[8:9]
	v_cndmask_b32_e64 v200, v230, v234, s[6:7]
	v_cndmask_b32_e64 v201, v240, v236, s[6:7]
	v_cndmask_b32_e64 v202, v199, v214, s[6:7]
	v_cndmask_b32_e64 v203, v228, v232, s[6:7]
	v_pk_fma_f32 v[204:205], v[134:135], v[204:205], v[142:143]
	v_pk_fma_f32 v[212:213], v[132:133], v[212:213], v[140:141]
	v_pk_fma_f32 v[200:201], v[130:131], v[200:201], v[204:205]
	v_pk_fma_f32 v[202:203], v[128:129], v[202:203], v[212:213]
	v_pk_fma_f32 v[90:91], v[90:91], v[138:139], v[200:201]
	v_pk_fma_f32 v[88:89], v[88:89], v[136:137], v[202:203]
	v_pk_mul_f32 v[86:87], v[86:87], v[206:207]
	v_pk_mul_f32 v[84:85], v[84:85], v[186:187]
	s_nop 1
	v_mov_b32_dpp v199, v84 row_ror:1 row_mask:0xf bank_mask:0xf
	v_mov_b32_dpp v206, v84 row_ror:2 row_mask:0xf bank_mask:0xf
	v_mov_b32_dpp v203, v85 row_ror:1 row_mask:0xf bank_mask:0xf
	v_mov_b32_dpp v207, v85 row_ror:2 row_mask:0xf bank_mask:0xf
	v_mov_b32_dpp v200, v86 row_ror:1 row_mask:0xf bank_mask:0xf
	v_mov_b32_dpp v204, v86 row_ror:2 row_mask:0xf bank_mask:0xf
	v_mov_b32_dpp v201, v87 row_ror:1 row_mask:0xf bank_mask:0xf
	v_mov_b32_dpp v205, v87 row_ror:2 row_mask:0xf bank_mask:0xf
	v_cndmask_b32_e64 v206, v215, v206, s[8:9]
	v_cndmask_b32_e64 v204, v235, v204, s[8:9]
	v_cndmask_b32_e64 v205, v237, v205, s[8:9]
	v_cndmask_b32_e64 v207, v233, v207, s[8:9]
	v_cndmask_b32_e64 v200, v234, v200, s[6:7]
	v_cndmask_b32_e64 v201, v236, v201, s[6:7]
	v_cndmask_b32_e64 v202, v214, v199, s[6:7]
	v_cndmask_b32_e64 v203, v232, v203, s[6:7]
	v_pk_fma_f32 v[134:135], v[134:135], v[204:205], v[142:143]
	v_pk_fma_f32 v[132:133], v[132:133], v[206:207], v[140:141]
	v_pk_fma_f32 v[130:131], v[130:131], v[200:201], v[134:135]
	v_pk_fma_f32 v[128:129], v[128:129], v[202:203], v[132:133]
	v_pk_fma_f32 v[86:87], v[86:87], v[138:139], v[130:131]
	v_pk_fma_f32 v[84:85], v[84:85], v[136:137], v[128:129]
	s_nop 0
	v_add_co_u32_e32 v136, vcc, 0x5000, v170
	global_load_dwordx4 v[132:135], v[208:209], off offset:2064
	global_load_dwordx4 v[128:131], v[210:211], off offset:2064
	v_addc_co_u32_e32 v137, vcc, 0, v171, vcc
	v_add_co_u32_e32 v140, vcc, 0x5000, v166
	global_load_dwordx4 v[136:139], v[136:137], off offset:2064
	s_nop 0
	v_addc_co_u32_e32 v141, vcc, 0, v167, vcc
	global_load_dwordx4 v[140:143], v[140:141], off offset:2064
	s_and_b64 vcc, exec, s[12:13]
	s_cbranch_vccnz .LBB0_1724
	ds_read_b128 v[198:201], v226 offset:528
	v_mov_b32_e32 v202, v196
	v_mov_b32_e32 v203, v196
	s_andn2_b64 s[0:1], s[0:1], exec
	s_waitcnt lgkmcnt(0)
	v_pk_mul_f32 v[202:203], v[202:203], v[200:201]
	v_pk_mul_f32 v[204:205], v[196:197], v[198:199]
	ds_read_b128 v[198:201], v179 offset:528
	v_mov_b32_e32 v196, v194
	v_mov_b32_e32 v197, v194
	s_waitcnt lgkmcnt(0)
	v_pk_mul_f32 v[196:197], v[196:197], v[200:201]
	v_pk_mul_f32 v[198:199], v[194:195], v[198:199]
	v_cndmask_b32_e64 v194, v196, v202, s[10:11]
	v_cndmask_b32_e64 v200, v197, v203, s[10:11]
	v_cndmask_b32_e64 v179, v198, v204, s[10:11]
	v_cndmask_b32_e64 v195, v199, v205, s[10:11]
	s_branch .LBB0_1725

; #define PG8_LAS __attribute__((address_space(3)))
; __device__ __forceinline__ float dpp_ror1(float x) { float r; asm volatile("s_nop 1\n\tv_mov_b32_dpp %0, %1 row_ror:1 row_mask:0xf bank_mask:0xf" : "=&v"(r) : "v"(x)); return r; }
; __device__ __forceinline__ float dpp_ror2(float x) { float r; asm volatile("s_nop 1\n\tv_mov_b32_dpp %0, %1 row_ror:2 row_mask:0xf bank_mask:0xf" : "=&v"(r) : "v"(x)); return r; }
;     __device__ __forceinline__ void operator()(f32x4 (&acc)[2][2][4][2], const Unit& u, int wr, int wc, int fr_, int fq_) const {
;     ...
;                 for (int n = 0; n < 2; ++n) {
;                     const int ct = bj * HALF + wc * 32 + 8 * fq + 4 * n;
;                     const int cidx = bj * 5632 + jcol + 4 * n;
;                     const f32x4 w0 = *(const f32x4*)(cw + cidx), w1 = *(const f32x4*)(cw + 11264 + cidx), w2 = *(const f32x4*)(cw + 22528 + cidx), b4 = *(const f32x4*)(cb + cidx);
;                     f32x4 pR1 = (f32x4){0.f, 0.f, 0.f, 0.f}, pR2 = pR1;
;                     if (blk) { const f32x4 h14 = *(const PG8_LAS f32x4*)(hal + ((blk - 1) * 2 + 0) * 256 + ct) * rs14, h15 = *(const PG8_LAS f32x4*)(hal + ((blk - 1) * 2 + 1) * 256 + ct) * rs15;
;                         pR1 = h15; pR2 = (fr == 0) ? h14 : h15; }
; #pragma unroll
;                     for (int m = 0; m < 4; ++m) {
;                         const f32x4 U = acc[ai][bj][m][n] * rsr[m];
;                         f32x4 R1, R2;
; #pragma unroll
;                         for (int i = 0; i < 4; ++i) { R1[i] = dpp_ror1(U[i]); R2[i] = dpp_ror2(U[i]); }
;                         const f32x4 U1 = (fr >= 1) ? R1 : pR1, U2 = (fr >= 2) ? R2 : pR2;
;                         const f32x4 C = b4 + w0 * U2 + w1 * U1 + w2 * U;
;                         acc[ai][bj][m][n] = C; pR1 = R1; pR2 = R2;
;                         asm volatile("" : "+v"(acc[ai][bj][m][n]));
;                         __builtin_amdgcn_sched_barrier(0);
;                     }
;                     asm volatile("" ::: "memory");
;                 }
;             if (ai == 0 && wr == 0 && fr < 2) {
; #pragma unroll
;                 for (int bj = 0; bj < 2; ++bj)
; #pragma unroll
;                     for (int n = 0; n < 2; ++n) *(f32x4*)(TOP + ((size_t)u.pm * 2 + fr) * 11264 + u.pn * BM + bj * HALF + wc * 32 + 8 * fq + 4 * n) = acc[0][bj][0][n]; }
.LBB0_1725:
	v_mov_b32_e32 v202, v192
	v_mov_b32_e32 v203, v192
	v_pk_mul_f32 v[78:79], v[78:79], v[202:203]
	v_pk_mul_f32 v[76:77], v[76:77], v[192:193]
	s_nop 0
	s_nop 1
	v_mov_b32_dpp v201, v76 row_ror:1 row_mask:0xf bank_mask:0xf
	v_mov_b32_dpp v202, v76 row_ror:2 row_mask:0xf bank_mask:0xf
	v_mov_b32_dpp v203, v77 row_ror:1 row_mask:0xf bank_mask:0xf
	v_mov_b32_dpp v204, v77 row_ror:2 row_mask:0xf bank_mask:0xf
	v_mov_b32_dpp v205, v78 row_ror:1 row_mask:0xf bank_mask:0xf
	v_mov_b32_dpp v206, v78 row_ror:2 row_mask:0xf bank_mask:0xf
	v_mov_b32_dpp v207, v79 row_ror:1 row_mask:0xf bank_mask:0xf
	v_mov_b32_dpp v208, v79 row_ror:2 row_mask:0xf bank_mask:0xf
	v_cndmask_b32_e64 v192, v196, v205, s[6:7]
	v_cndmask_b32_e64 v193, v197, v207, s[6:7]
	v_cndmask_b32_e64 v196, v198, v201, s[6:7]
	v_cndmask_b32_e64 v197, v199, v203, s[6:7]
	v_cndmask_b32_e64 v198, v194, v206, s[8:9]
	v_cndmask_b32_e64 v199, v200, v208, s[8:9]
	v_cndmask_b32_e64 v194, v179, v202, s[8:9]
	v_cndmask_b32_e64 v195, v195, v204, s[8:9]
	s_waitcnt vmcnt(0)
	v_pk_fma_f32 v[198:199], v[134:135], v[198:199], v[142:143]
	v_pk_fma_f32 v[194:195], v[132:133], v[194:195], v[140:141]
	v_pk_fma_f32 v[192:193], v[130:131], v[192:193], v[198:199]
	v_pk_fma_f32 v[194:195], v[128:129], v[196:197], v[194:195]
	v_pk_fma_f32 v[78:79], v[78:79], v[138:139], v[192:193]
	v_pk_fma_f32 v[76:77], v[76:77], v[136:137], v[194:195]
	v_mov_b32_e32 v192, v190
	v_mov_b32_e32 v193, v190
	v_pk_mul_f32 v[74:75], v[74:75], v[192:193]
	v_pk_mul_f32 v[72:73], v[72:73], v[190:191]
	s_nop 1
	v_mov_b32_dpp v179, v72 row_ror:1 row_mask:0xf bank_mask:0xf
	v_mov_b32_dpp v198, v72 row_ror:2 row_mask:0xf bank_mask:0xf
	v_mov_b32_dpp v199, v73 row_ror:1 row_mask:0xf bank_mask:0xf
	v_mov_b32_dpp v200, v73 row_ror:2 row_mask:0xf bank_mask:0xf
	v_mov_b32_dpp v209, v74 row_ror:1 row_mask:0xf bank_mask:0xf
	v_mov_b32_dpp v210, v74 row_ror:2 row_mask:0xf bank_mask:0xf
	v_mov_b32_dpp v211, v75 row_ror:1 row_mask:0xf bank_mask:0xf
	v_mov_b32_dpp v212, v75 row_ror:2 row_mask:0xf bank_mask:0xf
	v_cndmask_b32_e64 v196, v202, v198, s[8:9]
	v_cndmask_b32_e64 v194, v206, v210, s[8:9]
	v_cndmask_b32_e64 v195, v208, v212, s[8:9]
	v_cndmask_b32_e64 v197, v204, v200, s[8:9]
	v_cndmask_b32_e64 v190, v205, v209, s[6:7]
	v_cndmask_b32_e64 v191, v207, v211, s[6:7]
	v_cndmask_b32_e64 v192, v201, v179, s[6:7]
	v_cndmask_b32_e64 v193, v203, v199, s[6:7]
	v_pk_fma_f32 v[194:195], v[134:135], v[194:195], v[142:143]
	v_pk_fma_f32 v[196:197], v[132:133], v[196:197], v[140:141]
	v_pk_fma_f32 v[190:191], v[130:131], v[190:191], v[194:195]
	v_pk_fma_f32 v[192:193], v[128:129], v[192:193], v[196:197]
	v_pk_fma_f32 v[74:75], v[74:75], v[138:139], v[190:191]
	v_pk_fma_f32 v[72:73], v[72:73], v[136:137], v[192:193]
	v_mov_b32_e32 v190, v188
	v_mov_b32_e32 v191, v188
	v_pk_mul_f32 v[70:71], v[70:71], v[190:191]
	v_pk_mul_f32 v[68:69], v[68:69], v[188:189]
	s_nop 1
	v_mov_b32_dpp v196, v68 row_ror:1 row_mask:0xf bank_mask:0xf
	v_mov_b32_dpp v197, v68 row_ror:2 row_mask:0xf bank_mask:0xf
	v_mov_b32_dpp v201, v69 row_ror:1 row_mask:0xf bank_mask:0xf
	v_mov_b32_dpp v202, v69 row_ror:2 row_mask:0xf bank_mask:0xf
	v_mov_b32_dpp v203, v70 row_ror:1 row_mask:0xf bank_mask:0xf
	v_mov_b32_dpp v204, v70 row_ror:2 row_mask:0xf bank_mask:0xf
	v_mov_b32_dpp v205, v71 row_ror:1 row_mask:0xf bank_mask:0xf
	v_mov_b32_dpp v206, v71 row_ror:2 row_mask:0xf bank_mask:0xf
	v_cndmask_b32_e64 v194, v198, v197, s[8:9]
	v_cndmask_b32_e64 v192, v210, v204, s[8:9]
	v_cndmask_b32_e64 v193, v212, v206, s[8:9]
	v_cndmask_b32_e64 v195, v200, v202, s[8:9]
	v_cndmask_b32_e64 v188, v209, v203, s[6:7]
	v_cndmask_b32_e64 v189, v211, v205, s[6:7]
	v_cndmask_b32_e64 v190, v179, v196, s[6:7]
	v_cndmask_b32_e64 v191, v199, v201, s[6:7]
	v_pk_fma_f32 v[192:193], v[134:135], v[192:193], v[142:143]
	v_pk_fma_f32 v[194:195], v[132:133], v[194:195], v[140:141]
	v_pk_fma_f32 v[188:189], v[130:131], v[188:189], v[192:193]
	v_pk_fma_f32 v[190:191], v[128:129], v[190:191], v[194:195]
	v_pk_fma_f32 v[70:71], v[70:71], v[138:139], v[188:189]
	v_pk_fma_f32 v[68:69], v[68:69], v[136:137], v[190:191]
	v_mov_b32_e32 v188, v186
	v_mov_b32_e32 v189, v186
	v_pk_mul_f32 v[66:67], v[66:67], v[188:189]
	v_pk_mul_f32 v[64:65], v[64:65], v[186:187]
	s_nop 1
	v_mov_b32_dpp v179, v64 row_ror:1 row_mask:0xf bank_mask:0xf
	v_mov_b32_dpp v192, v64 row_ror:2 row_mask:0xf bank_mask:0xf
	v_mov_b32_dpp v189, v65 row_ror:1 row_mask:0xf bank_mask:0xf
	v_mov_b32_dpp v193, v65 row_ror:2 row_mask:0xf bank_mask:0xf
	v_mov_b32_dpp v186, v66 row_ror:1 row_mask:0xf bank_mask:0xf
	v_mov_b32_dpp v190, v66 row_ror:2 row_mask:0xf bank_mask:0xf
	v_mov_b32_dpp v187, v67 row_ror:1 row_mask:0xf bank_mask:0xf
	v_mov_b32_dpp v191, v67 row_ror:2 row_mask:0xf bank_mask:0xf
	v_cndmask_b32_e64 v192, v197, v192, s[8:9]
	v_cndmask_b32_e64 v190, v204, v190, s[8:9]
	v_cndmask_b32_e64 v191, v206, v191, s[8:9]
	v_cndmask_b32_e64 v193, v202, v193, s[8:9]
	v_cndmask_b32_e64 v186, v203, v186, s[6:7]
	v_cndmask_b32_e64 v187, v205, v187, s[6:7]
	v_cndmask_b32_e64 v188, v196, v179, s[6:7]
	v_cndmask_b32_e64 v189, v201, v189, s[6:7]
	v_pk_fma_f32 v[134:135], v[134:135], v[190:191], v[142:143]
	v_pk_fma_f32 v[132:133], v[132:133], v[192:193], v[140:141]
	v_pk_fma_f32 v[130:131], v[130:131], v[186:187], v[134:135]
	v_pk_fma_f32 v[128:129], v[128:129], v[188:189], v[132:133]
	v_pk_fma_f32 v[66:67], v[66:67], v[138:139], v[130:131]
	v_pk_fma_f32 v[64:65], v[64:65], v[136:137], v[128:129]
	s_nop 0
	s_and_saveexec_b64 s[12:13], s[0:1]
	s_cbranch_execz .LBB0_1727
	v_readlane_b32 s0, v244, 49
	v_ashrrev_i32_e32 v179, 31, v178
	v_readlane_b32 s1, v244, 50
	v_lshl_add_u64 v[128:129], v[184:185], 0, v[178:179]
	s_mov_b32 s16, 0xb000
	v_mov_b64_e32 v[130:131], s[0:1]
	v_mad_u64_u32 v[130:131], s[0:1], v128, s16, v[130:131]
	v_mov_b32_e32 v128, v131
	v_mad_u64_u32 v[128:129], s[0:1], v129, s16, v[128:129]
	v_mov_b32_e32 v131, v128
	v_lshl_add_u64 v[128:129], v[182:183], 2, v[130:131]
	s_lshl_b32 s16, s33, 2
	v_lshl_add_u64 v[128:129], v[128:129], 0, s[16:17]
	v_lshl_add_u64 v[128:129], v[176:177], 2, v[128:129]
	global_store_dwordx4 v[128:129], v[124:127], off
	global_store_dwordx4 v[128:129], v[116:119], off offset:16
	global_store_dwordx4 v[128:129], v[100:103], off offset:512
	global_store_dwordx4 v[128:129], v[76:79], off offset:528
; __device__ __forceinline__ u32x4 pack8(f32x4 v0, f32x4 v1) { u32x4 w; w.x = cvt_pk_bf16(v0[0], v0[1]); w.y = cvt_pk_bf16(v0[2], v0[3]); w.z = cvt_pk_bf16(v1[0], v1[1]); w.w = cvt_pk_bf16(v1[2], v1[3]); return w; }
; __device__ __forceinline__ f32x4 gelu4(f32x4 v) { f32x2 a = gelu_pk((f32x2){v[0], v[1]}), b = gelu_pk((f32x2){v[2], v[3]}); return (f32x4){a.x, a.y, b.x, b.y}; }
; __device__ __forceinline__ f32x2 gelu_pk(f32x2 v) {
;     const f32x2 av = __builtin_elementwise_abs(v), d = av * 0.2316418882f + 1.0f;
;     f32x2 t; t.x = __builtin_amdgcn_rcpf(d.x); t.y = __builtin_amdgcn_rcpf(d.y);
;     f32x2 q = t * 0.5307027145f + (-0.7265760135f); q = q * t + 0.7107068705f; q = q * t + (-0.142248368f); q = q * t + 0.127414796f; q = q * t;
;     const f32x2 s = (v * v) * (-0.72134752044f);
;     f32x2 e; e.x = __builtin_amdgcn_exp2f(s.x); e.y = __builtin_amdgcn_exp2f(s.y);
;     const f32x2 m = v * (q * e), r = v - m;
;     f32x2 o; o.x = v.x < 0.f ? m.x : r.x; o.y = v.y < 0.f ? m.y : r.y; return o;
;     __device__ __forceinline__ void operator()(f32x4 (&acc)[2][2][4][2], const Unit& u, int wr, int wc, int fr_, int fq_) const {
;     ...
;             for (int m = 0; m < 4; ++m) { const int row = u.pm * BM + blk * 64 + m * 16 + fr;
;                 const f32x4 g0 = gelu4(acc[ai][0][m][0]), g1 = gelu4(acc[ai][0][m][1]);
;                 *(u32x4*)(ACT + (size_t)row * 5632 + jcol) = pack8(g0 * acc[ai][1][m][0], g1 * acc[ai][1][m][1]); asm volatile("" ::: "memory"); __builtin_amdgcn_sched_barrier(0); }
.LBB0_1727:
	s_or_b64 exec, exec, s[12:13]
	v_and_b32_e32 v129, 0x7fffffff, v125
	v_and_b32_e32 v128, 0x7fffffff, v124
	v_pk_fma_f32 v[128:129], v[128:129], s[58:59], 1.0 op_sel_hi:[1,0,0]
	v_lshl_add_u32 v178, s90, 8, v178
	v_rcp_f32_e32 v182, v128
	v_rcp_f32_e32 v183, v129
	v_readlane_b32 s0, v244, 55
	v_pk_mul_f32 v[186:187], v[124:125], v[124:125]
	v_cmp_gt_f32_e32 vcc, 0, v124
	v_add_u32_e32 v179, s0, v178
	s_mov_b32 s0, 0xbf3a00e3
	v_mov_b64_e32 v[128:129], s[0:1]
	v_pk_fma_f32 v[184:185], v[182:183], s[60:61], v[128:129] op_sel_hi:[1,0,0]
	v_pk_mul_f32 v[186:187], v[186:187], s[50:51] op_sel_hi:[1,0]
	v_pk_fma_f32 v[184:185], v[182:183], v[184:185], s[62:63] op_sel_hi:[1,1,0]
	v_exp_f32_e32 v186, v186
	v_exp_f32_e32 v187, v187
	v_pk_fma_f32 v[184:185], v[182:183], v[184:185], s[64:65] op_sel_hi:[1,1,0]
	v_lshl_add_u64 v[138:139], v[164:165], 0, s[54:55]
	v_pk_fma_f32 v[184:185], v[182:183], v[184:185], s[66:67] op_sel_hi:[1,1,0]
	v_lshl_add_u64 v[140:141], v[168:169], 0, s[54:55]
	v_pk_mul_f32 v[182:183], v[182:183], v[184:185]
	v_pk_mul_f32 v[184:185], v[126:127], v[126:127]
	v_pk_mul_f32 v[182:183], v[186:187], v[182:183]
	v_pk_mul_f32 v[184:185], v[184:185], s[50:51] op_sel_hi:[1,0]
	v_pk_mul_f32 v[186:187], v[124:125], v[182:183]
	v_pk_fma_f32 v[182:183], v[124:125], v[182:183], v[124:125] neg_lo:[1,0,0] neg_hi:[1,0,0]
	v_exp_f32_e32 v184, v184
	v_cndmask_b32_e32 v124, v182, v186, vcc
	v_cmp_gt_f32_e32 vcc, 0, v125
	v_and_b32_e32 v182, 0x7fffffff, v126
	v_exp_f32_e32 v185, v185
	v_cndmask_b32_e32 v125, v183, v187, vcc
	v_and_b32_e32 v183, 0x7fffffff, v127
	v_pk_fma_f32 v[182:183], v[182:183], s[58:59], 1.0 op_sel_hi:[1,0,0]
	v_cmp_gt_f32_e32 vcc, 0, v126
	v_rcp_f32_e32 v182, v182
	v_rcp_f32_e32 v183, v183
	v_pk_mul_f32 v[100:101], v[124:125], v[100:101]
	v_lshl_add_u64 v[142:143], v[170:171], 0, s[54:55]
	v_cvt_pk_bf16_f32 v100, v100, v101
	v_pk_fma_f32 v[186:187], v[182:183], s[60:61], v[128:129] op_sel_hi:[1,0,0]
	v_lshl_add_u64 v[176:177], v[166:167], 0, s[54:55]
	v_pk_fma_f32 v[186:187], v[182:183], v[186:187], s[62:63] op_sel_hi:[1,1,0]
	v_lshl_add_u64 v[130:131], v[164:165], 0, s[56:57]
	v_pk_fma_f32 v[186:187], v[182:183], v[186:187], s[64:65] op_sel_hi:[1,1,0]
	v_lshl_add_u64 v[132:133], v[168:169], 0, s[56:57]
	v_pk_fma_f32 v[186:187], v[182:183], v[186:187], s[66:67] op_sel_hi:[1,1,0]
	v_lshl_add_u64 v[134:135], v[170:171], 0, s[56:57]
	v_pk_mul_f32 v[182:183], v[182:183], v[186:187]
	v_pk_mul_f32 v[186:187], v[116:117], v[116:117]
	v_pk_mul_f32 v[182:183], v[184:185], v[182:183]
	v_pk_mul_f32 v[186:187], v[186:187], s[50:51] op_sel_hi:[1,0]
	v_pk_mul_f32 v[184:185], v[126:127], v[182:183]
	v_pk_fma_f32 v[182:183], v[126:127], v[182:183], v[126:127] neg_lo:[1,0,0] neg_hi:[1,0,0]
	v_exp_f32_e32 v186, v186
	v_cndmask_b32_e32 v126, v182, v184, vcc
	v_cmp_gt_f32_e32 vcc, 0, v127
	v_and_b32_e32 v182, 0x7fffffff, v116
	v_exp_f32_e32 v187, v187
	v_cndmask_b32_e32 v127, v183, v185, vcc
	v_and_b32_e32 v183, 0x7fffffff, v117
	v_pk_fma_f32 v[182:183], v[182:183], s[58:59], 1.0 op_sel_hi:[1,0,0]
	v_cmp_gt_f32_e32 vcc, 0, v116
	v_rcp_f32_e32 v182, v182
	v_rcp_f32_e32 v183, v183
	v_pk_mul_f32 v[102:103], v[126:127], v[102:103]
	v_lshl_add_u64 v[136:137], v[166:167], 0, s[56:57]
	v_cvt_pk_bf16_f32 v101, v102, v103
	v_pk_fma_f32 v[184:185], v[182:183], s[60:61], v[128:129] op_sel_hi:[1,0,0]
	s_nop 0
	v_pk_fma_f32 v[184:185], v[182:183], v[184:185], s[62:63] op_sel_hi:[1,1,0]
	s_nop 0
	v_pk_fma_f32 v[184:185], v[182:183], v[184:185], s[64:65] op_sel_hi:[1,1,0]
	s_nop 0
	v_pk_fma_f32 v[184:185], v[182:183], v[184:185], s[66:67] op_sel_hi:[1,1,0]
	s_nop 0
	v_pk_mul_f32 v[182:183], v[182:183], v[184:185]
	v_pk_mul_f32 v[184:185], v[118:119], v[118:119]
	v_pk_mul_f32 v[182:183], v[186:187], v[182:183]
	v_pk_mul_f32 v[184:185], v[184:185], s[50:51] op_sel_hi:[1,0]
	v_pk_mul_f32 v[186:187], v[116:117], v[182:183]
	v_pk_fma_f32 v[182:183], v[116:117], v[182:183], v[116:117] neg_lo:[1,0,0] neg_hi:[1,0,0]
	v_exp_f32_e32 v184, v184
	v_cndmask_b32_e32 v116, v182, v186, vcc
	v_cmp_gt_f32_e32 vcc, 0, v117
	v_and_b32_e32 v182, 0x7fffffff, v118
	v_exp_f32_e32 v185, v185
	v_cndmask_b32_e32 v117, v183, v187, vcc
	v_and_b32_e32 v183, 0x7fffffff, v119
	v_pk_fma_f32 v[182:183], v[182:183], s[58:59], 1.0 op_sel_hi:[1,0,0]
	v_cmp_gt_f32_e32 vcc, 0, v118
	v_rcp_f32_e32 v182, v182
	v_rcp_f32_e32 v183, v183
	v_pk_mul_f32 v[76:77], v[116:117], v[76:77]
	v_pk_fma_f32 v[186:187], v[182:183], s[60:61], v[128:129] op_sel_hi:[1,0,0]
	s_nop 0
	v_pk_fma_f32 v[186:187], v[182:183], v[186:187], s[62:63] op_sel_hi:[1,1,0]
	v_cvt_pk_bf16_f32 v102, v76, v77
	v_pk_fma_f32 v[186:187], v[182:183], v[186:187], s[64:65] op_sel_hi:[1,1,0]
	v_mov_b64_e32 v[76:77], s[22:23]
	v_pk_fma_f32 v[186:187], v[182:183], v[186:187], s[66:67] op_sel_hi:[1,1,0]
	v_mad_i64_i32 v[116:117], s[0:1], v179, s93, v[76:77]
	v_pk_mul_f32 v[182:183], v[182:183], v[186:187]
	s_nop 0
	v_pk_mul_f32 v[182:183], v[184:185], v[182:183]
	s_nop 0
	v_pk_mul_f32 v[184:185], v[118:119], v[182:183]
	v_pk_fma_f32 v[182:183], v[118:119], v[182:183], v[118:119] neg_lo:[1,0,0] neg_hi:[1,0,0]
	s_nop 0
	v_cndmask_b32_e32 v118, v182, v184, vcc
	v_cmp_gt_f32_e32 vcc, 0, v119
	s_nop 1
	v_cndmask_b32_e32 v119, v183, v185, vcc
	v_pk_mul_f32 v[78:79], v[118:119], v[78:79]
	s_nop 0
	v_cvt_pk_bf16_f32 v103, v78, v79
	v_lshlrev_b64 v[78:79], 1, v[180:181]
	v_lshl_add_u64 v[116:117], v[116:117], 0, v[78:79]
	global_store_dwordx4 v[116:117], v[100:103], off
	s_nop 1
	v_and_b32_e32 v101, 0x7fffffff, v121
	v_and_b32_e32 v100, 0x7fffffff, v120
	v_pk_fma_f32 v[100:101], v[100:101], s[58:59], 1.0 op_sel_hi:[1,0,0]
; __device__ __forceinline__ u32x4 pack8(f32x4 v0, f32x4 v1) { u32x4 w; w.x = cvt_pk_bf16(v0[0], v0[1]); w.y = cvt_pk_bf16(v0[2], v0[3]); w.z = cvt_pk_bf16(v1[0], v1[1]); w.w = cvt_pk_bf16(v1[2], v1[3]); return w; }
; __device__ __forceinline__ f32x4 gelu4(f32x4 v) { f32x2 a = gelu_pk((f32x2){v[0], v[1]}), b = gelu_pk((f32x2){v[2], v[3]}); return (f32x4){a.x, a.y, b.x, b.y}; }
; __device__ __forceinline__ f32x2 gelu_pk(f32x2 v) {
;     const f32x2 av = __builtin_elementwise_abs(v), d = av * 0.2316418882f + 1.0f;
;     f32x2 t; t.x = __builtin_amdgcn_rcpf(d.x); t.y = __builtin_amdgcn_rcpf(d.y);
;     f32x2 q = t * 0.5307027145f + (-0.7265760135f); q = q * t + 0.7107068705f; q = q * t + (-0.142248368f); q = q * t + 0.127414796f; q = q * t;
;     const f32x2 s = (v * v) * (-0.72134752044f);
;     f32x2 e; e.x = __builtin_amdgcn_exp2f(s.x); e.y = __builtin_amdgcn_exp2f(s.y);
;     const f32x2 m = v * (q * e), r = v - m;
;     f32x2 o; o.x = v.x < 0.f ? m.x : r.x; o.y = v.y < 0.f ? m.y : r.y; return o;
;     __device__ __forceinline__ void operator()(f32x4 (&acc)[2][2][4][2], const Unit& u, int wr, int wc, int fr_, int fq_) const {
;     ...
;             for (int m = 0; m < 4; ++m) { const int row = u.pm * BM + blk * 64 + m * 16 + fr;
;                 const f32x4 g0 = gelu4(acc[ai][0][m][0]), g1 = gelu4(acc[ai][0][m][1]);
;                 *(u32x4*)(ACT + (size_t)row * 5632 + jcol) = pack8(g0 * acc[ai][1][m][0], g1 * acc[ai][1][m][1]); asm volatile("" ::: "memory"); __builtin_amdgcn_sched_barrier(0); }
	v_pk_mul_f32 v[116:117], v[120:121], v[120:121]
	v_rcp_f32_e32 v100, v100
	v_rcp_f32_e32 v101, v101
	v_pk_mul_f32 v[116:117], v[116:117], s[50:51] op_sel_hi:[1,0]
	v_cmp_gt_f32_e32 vcc, 0, v120
	v_exp_f32_e32 v116, v116
	v_pk_fma_f32 v[102:103], v[100:101], s[60:61], v[128:129] op_sel_hi:[1,0,0]
	v_exp_f32_e32 v117, v117
	v_pk_fma_f32 v[102:103], v[100:101], v[102:103], s[62:63] op_sel_hi:[1,1,0]
	v_add_u32_e32 v124, 16, v179
	v_pk_fma_f32 v[102:103], v[100:101], v[102:103], s[64:65] op_sel_hi:[1,1,0]
	s_nop 0
	v_pk_fma_f32 v[102:103], v[100:101], v[102:103], s[66:67] op_sel_hi:[1,1,0]
	s_nop 0
	v_pk_mul_f32 v[100:101], v[100:101], v[102:103]
	v_pk_mul_f32 v[102:103], v[122:123], v[122:123]
	v_pk_mul_f32 v[100:101], v[116:117], v[100:101]
	v_pk_mul_f32 v[102:103], v[102:103], s[50:51] op_sel_hi:[1,0]
	v_pk_mul_f32 v[116:117], v[120:121], v[100:101]
	v_pk_fma_f32 v[100:101], v[120:121], v[100:101], v[120:121] neg_lo:[1,0,0] neg_hi:[1,0,0]
	v_exp_f32_e32 v102, v102
	v_cndmask_b32_e32 v100, v100, v116, vcc
	v_cmp_gt_f32_e32 vcc, 0, v121
	v_and_b32_e32 v116, 0x7fffffff, v122
	v_exp_f32_e32 v103, v103
	v_cndmask_b32_e32 v101, v101, v117, vcc
	v_and_b32_e32 v117, 0x7fffffff, v123
	v_pk_fma_f32 v[116:117], v[116:117], s[58:59], 1.0 op_sel_hi:[1,0,0]
	v_cmp_gt_f32_e32 vcc, 0, v122
	v_rcp_f32_e32 v116, v116
	v_rcp_f32_e32 v117, v117
	v_pk_mul_f32 v[120:121], v[112:113], v[112:113]
	v_pk_mul_f32 v[96:97], v[100:101], v[96:97]
	v_pk_mul_f32 v[120:121], v[120:121], s[50:51] op_sel_hi:[1,0]
	v_pk_fma_f32 v[118:119], v[116:117], s[60:61], v[128:129] op_sel_hi:[1,0,0]
	v_exp_f32_e32 v120, v120
	v_pk_fma_f32 v[118:119], v[116:117], v[118:119], s[62:63] op_sel_hi:[1,1,0]
	v_exp_f32_e32 v121, v121
	v_pk_fma_f32 v[118:119], v[116:117], v[118:119], s[64:65] op_sel_hi:[1,1,0]
	s_nop 0
	v_pk_fma_f32 v[118:119], v[116:117], v[118:119], s[66:67] op_sel_hi:[1,1,0]
	s_nop 0
	v_pk_mul_f32 v[116:117], v[116:117], v[118:119]
	s_nop 0
	v_pk_mul_f32 v[102:103], v[102:103], v[116:117]
	s_nop 0
	v_pk_mul_f32 v[116:117], v[122:123], v[102:103]
	v_pk_fma_f32 v[102:103], v[122:123], v[102:103], v[122:123] neg_lo:[1,0,0] neg_hi:[1,0,0]
	s_nop 0
	v_cndmask_b32_e32 v102, v102, v116, vcc
	v_cmp_gt_f32_e32 vcc, 0, v123
	v_and_b32_e32 v116, 0x7fffffff, v112
	s_nop 0
	v_cndmask_b32_e32 v103, v103, v117, vcc
	v_and_b32_e32 v117, 0x7fffffff, v113
	v_pk_fma_f32 v[116:117], v[116:117], s[58:59], 1.0 op_sel_hi:[1,0,0]
	v_cmp_gt_f32_e32 vcc, 0, v112
	v_rcp_f32_e32 v116, v116
	v_rcp_f32_e32 v117, v117
	v_pk_mul_f32 v[98:99], v[102:103], v[98:99]
	v_pk_fma_f32 v[118:119], v[116:117], s[60:61], v[128:129] op_sel_hi:[1,0,0]
	s_nop 0
	v_pk_fma_f32 v[118:119], v[116:117], v[118:119], s[62:63] op_sel_hi:[1,1,0]
	s_nop 0
	v_pk_fma_f32 v[118:119], v[116:117], v[118:119], s[64:65] op_sel_hi:[1,1,0]
	s_nop 0
	v_pk_fma_f32 v[118:119], v[116:117], v[118:119], s[66:67] op_sel_hi:[1,1,0]
	s_nop 0
	v_pk_mul_f32 v[116:117], v[116:117], v[118:119]
	v_pk_mul_f32 v[118:119], v[114:115], v[114:115]
	v_pk_mul_f32 v[116:117], v[120:121], v[116:117]
	v_pk_mul_f32 v[118:119], v[118:119], s[50:51] op_sel_hi:[1,0]
	v_pk_mul_f32 v[120:121], v[112:113], v[116:117]
	v_pk_fma_f32 v[116:117], v[112:113], v[116:117], v[112:113] neg_lo:[1,0,0] neg_hi:[1,0,0]
	v_exp_f32_e32 v118, v118
	v_cndmask_b32_e32 v112, v116, v120, vcc
	v_cmp_gt_f32_e32 vcc, 0, v113
	v_and_b32_e32 v116, 0x7fffffff, v114
	v_exp_f32_e32 v119, v119
	v_cndmask_b32_e32 v113, v117, v121, vcc
	v_and_b32_e32 v117, 0x7fffffff, v115
	v_pk_fma_f32 v[116:117], v[116:117], s[58:59], 1.0 op_sel_hi:[1,0,0]
	v_cmp_gt_f32_e32 vcc, 0, v114
	v_rcp_f32_e32 v116, v116
	v_rcp_f32_e32 v117, v117
	s_nop 0
	v_pk_fma_f32 v[120:121], v[116:117], s[60:61], v[128:129] op_sel_hi:[1,0,0]
	s_nop 0
	v_pk_fma_f32 v[120:121], v[116:117], v[120:121], s[62:63] op_sel_hi:[1,1,0]
	s_nop 0
	v_pk_fma_f32 v[120:121], v[116:117], v[120:121], s[64:65] op_sel_hi:[1,1,0]
	s_nop 0
	v_pk_fma_f32 v[120:121], v[116:117], v[120:121], s[66:67] op_sel_hi:[1,1,0]
	s_nop 0
	v_pk_mul_f32 v[116:117], v[116:117], v[120:121]
	s_nop 0
	v_pk_mul_f32 v[116:117], v[118:119], v[116:117]
	s_nop 0
	v_pk_mul_f32 v[118:119], v[114:115], v[116:117]
	v_pk_fma_f32 v[116:117], v[114:115], v[116:117], v[114:115] neg_lo:[1,0,0] neg_hi:[1,0,0]
	s_nop 0
	v_cndmask_b32_e32 v114, v116, v118, vcc
	v_cmp_gt_f32_e32 vcc, 0, v115
	s_nop 1
	v_cndmask_b32_e32 v115, v117, v119, vcc
	v_pk_mul_f32 v[100:101], v[114:115], v[74:75]
	v_pk_mul_f32 v[74:75], v[112:113], v[72:73]
	v_cvt_pk_bf16_f32 v72, v96, v97
	v_mad_i64_i32 v[96:97], s[0:1], v124, s93, v[76:77]
	v_cvt_pk_bf16_f32 v73, v98, v99
	v_cvt_pk_bf16_f32 v74, v74, v75
	v_cvt_pk_bf16_f32 v75, v100, v101
	v_lshl_add_u64 v[96:97], v[96:97], 0, v[78:79]
	global_store_dwordx4 v[96:97], v[72:75], off
	s_nop 1
	v_and_b32_e32 v73, 0x7fffffff, v105
	v_and_b32_e32 v72, 0x7fffffff, v104
	v_pk_fma_f32 v[72:73], v[72:73], s[58:59], 1.0 op_sel_hi:[1,0,0]
	v_pk_mul_f32 v[96:97], v[104:105], v[104:105]
	v_rcp_f32_e32 v72, v72
	v_rcp_f32_e32 v73, v73
	v_pk_mul_f32 v[96:97], v[96:97], s[50:51] op_sel_hi:[1,0]
	v_cmp_gt_f32_e32 vcc, 0, v104
	v_exp_f32_e32 v96, v96
	v_pk_fma_f32 v[74:75], v[72:73], s[60:61], v[128:129] op_sel_hi:[1,0,0]
	v_exp_f32_e32 v97, v97
	v_pk_fma_f32 v[74:75], v[72:73], v[74:75], s[62:63] op_sel_hi:[1,1,0]
	v_pk_mul_f32 v[100:101], v[108:109], v[108:109]
	v_pk_fma_f32 v[74:75], v[72:73], v[74:75], s[64:65] op_sel_hi:[1,1,0]
	v_pk_mul_f32 v[100:101], v[100:101], s[50:51] op_sel_hi:[1,0]
	v_pk_fma_f32 v[74:75], v[72:73], v[74:75], s[66:67] op_sel_hi:[1,1,0]
	v_exp_f32_e32 v100, v100
	v_pk_mul_f32 v[72:73], v[72:73], v[74:75]
	v_pk_mul_f32 v[74:75], v[106:107], v[106:107]
; __device__ __forceinline__ u32x4 pack8(f32x4 v0, f32x4 v1) { u32x4 w; w.x = cvt_pk_bf16(v0[0], v0[1]); w.y = cvt_pk_bf16(v0[2], v0[3]); w.z = cvt_pk_bf16(v1[0], v1[1]); w.w = cvt_pk_bf16(v1[2], v1[3]); return w; }
; __device__ __forceinline__ f32x4 gelu4(f32x4 v) { f32x2 a = gelu_pk((f32x2){v[0], v[1]}), b = gelu_pk((f32x2){v[2], v[3]}); return (f32x4){a.x, a.y, b.x, b.y}; }
; __device__ __forceinline__ f32x2 gelu_pk(f32x2 v) {
;     const f32x2 av = __builtin_elementwise_abs(v), d = av * 0.2316418882f + 1.0f;
;     f32x2 t; t.x = __builtin_amdgcn_rcpf(d.x); t.y = __builtin_amdgcn_rcpf(d.y);
;     f32x2 q = t * 0.5307027145f + (-0.7265760135f); q = q * t + 0.7107068705f; q = q * t + (-0.142248368f); q = q * t + 0.127414796f; q = q * t;
;     const f32x2 s = (v * v) * (-0.72134752044f);
;     f32x2 e; e.x = __builtin_amdgcn_exp2f(s.x); e.y = __builtin_amdgcn_exp2f(s.y);
;     const f32x2 m = v * (q * e), r = v - m;
;     f32x2 o; o.x = v.x < 0.f ? m.x : r.x; o.y = v.y < 0.f ? m.y : r.y; return o;
;     __device__ __forceinline__ void operator()(f32x4 (&acc)[2][2][4][2], const Unit& u, int wr, int wc, int fr_, int fq_) const {
;     ...
;             for (int m = 0; m < 4; ++m) { const int row = u.pm * BM + blk * 64 + m * 16 + fr;
;                 const f32x4 g0 = gelu4(acc[ai][0][m][0]), g1 = gelu4(acc[ai][0][m][1]);
;                 *(u32x4*)(ACT + (size_t)row * 5632 + jcol) = pack8(g0 * acc[ai][1][m][0], g1 * acc[ai][1][m][1]); asm volatile("" ::: "memory"); __builtin_amdgcn_sched_barrier(0); }
	v_pk_mul_f32 v[72:73], v[96:97], v[72:73]
	v_pk_mul_f32 v[74:75], v[74:75], s[50:51] op_sel_hi:[1,0]
	v_pk_mul_f32 v[96:97], v[104:105], v[72:73]
	v_pk_fma_f32 v[72:73], v[104:105], v[72:73], v[104:105] neg_lo:[1,0,0] neg_hi:[1,0,0]
	v_exp_f32_e32 v74, v74
	v_cndmask_b32_e32 v72, v72, v96, vcc
	v_cmp_gt_f32_e32 vcc, 0, v105
	v_and_b32_e32 v96, 0x7fffffff, v106
	v_exp_f32_e32 v75, v75
	v_cndmask_b32_e32 v73, v73, v97, vcc
	v_and_b32_e32 v97, 0x7fffffff, v107
	v_pk_fma_f32 v[96:97], v[96:97], s[58:59], 1.0 op_sel_hi:[1,0,0]
	v_cmp_gt_f32_e32 vcc, 0, v106
	v_rcp_f32_e32 v96, v96
	v_rcp_f32_e32 v97, v97
	v_exp_f32_e32 v101, v101
	v_add_u32_e32 v112, 32, v179
	v_pk_mul_f32 v[72:73], v[72:73], v[88:89]
	v_pk_fma_f32 v[98:99], v[96:97], s[60:61], v[128:129] op_sel_hi:[1,0,0]
	s_nop 0
	v_pk_fma_f32 v[98:99], v[96:97], v[98:99], s[62:63] op_sel_hi:[1,1,0]
	s_nop 0
	v_pk_fma_f32 v[98:99], v[96:97], v[98:99], s[64:65] op_sel_hi:[1,1,0]
	s_nop 0
	v_pk_fma_f32 v[98:99], v[96:97], v[98:99], s[66:67] op_sel_hi:[1,1,0]
	s_nop 0
	v_pk_mul_f32 v[96:97], v[96:97], v[98:99]
	s_nop 0
	v_pk_mul_f32 v[74:75], v[74:75], v[96:97]
	s_nop 0
	v_pk_mul_f32 v[96:97], v[106:107], v[74:75]
	v_pk_fma_f32 v[74:75], v[106:107], v[74:75], v[106:107] neg_lo:[1,0,0] neg_hi:[1,0,0]
	s_nop 0
	v_cndmask_b32_e32 v74, v74, v96, vcc
	v_cmp_gt_f32_e32 vcc, 0, v107
	v_and_b32_e32 v96, 0x7fffffff, v108
	s_nop 0
	v_cndmask_b32_e32 v75, v75, v97, vcc
	v_and_b32_e32 v97, 0x7fffffff, v109
	v_pk_fma_f32 v[96:97], v[96:97], s[58:59], 1.0 op_sel_hi:[1,0,0]
	v_cmp_gt_f32_e32 vcc, 0, v108
	v_rcp_f32_e32 v96, v96
	v_rcp_f32_e32 v97, v97
	v_pk_mul_f32 v[74:75], v[74:75], v[90:91]
	v_pk_fma_f32 v[98:99], v[96:97], s[60:61], v[128:129] op_sel_hi:[1,0,0]
	s_nop 0
	v_pk_fma_f32 v[98:99], v[96:97], v[98:99], s[62:63] op_sel_hi:[1,1,0]
	s_nop 0
	v_pk_fma_f32 v[98:99], v[96:97], v[98:99], s[64:65] op_sel_hi:[1,1,0]
	s_nop 0
	v_pk_fma_f32 v[98:99], v[96:97], v[98:99], s[66:67] op_sel_hi:[1,1,0]
	s_nop 0
	v_pk_mul_f32 v[96:97], v[96:97], v[98:99]
	v_pk_mul_f32 v[98:99], v[110:111], v[110:111]
	v_pk_mul_f32 v[96:97], v[100:101], v[96:97]
	v_pk_mul_f32 v[98:99], v[98:99], s[50:51] op_sel_hi:[1,0]
	v_pk_mul_f32 v[100:101], v[108:109], v[96:97]
	v_pk_fma_f32 v[96:97], v[108:109], v[96:97], v[108:109] neg_lo:[1,0,0] neg_hi:[1,0,0]
	v_exp_f32_e32 v98, v98
	v_cndmask_b32_e32 v96, v96, v100, vcc
	v_cmp_gt_f32_e32 vcc, 0, v109
	v_and_b32_e32 v100, 0x7fffffff, v110
	v_exp_f32_e32 v99, v99
	v_cndmask_b32_e32 v97, v97, v101, vcc
	v_and_b32_e32 v101, 0x7fffffff, v111
	v_pk_fma_f32 v[100:101], v[100:101], s[58:59], 1.0 op_sel_hi:[1,0,0]
	v_cmp_gt_f32_e32 vcc, 0, v110
	v_rcp_f32_e32 v100, v100
	v_rcp_f32_e32 v101, v101
	s_nop 0
	v_pk_fma_f32 v[102:103], v[100:101], s[60:61], v[128:129] op_sel_hi:[1,0,0]
	s_nop 0
	v_pk_fma_f32 v[102:103], v[100:101], v[102:103], s[62:63] op_sel_hi:[1,1,0]
	s_nop 0
	v_pk_fma_f32 v[102:103], v[100:101], v[102:103], s[64:65] op_sel_hi:[1,1,0]
	s_nop 0
	v_pk_fma_f32 v[102:103], v[100:101], v[102:103], s[66:67] op_sel_hi:[1,1,0]
	s_nop 0
	v_pk_mul_f32 v[100:101], v[100:101], v[102:103]
	s_nop 0
	v_pk_mul_f32 v[98:99], v[98:99], v[100:101]
	s_nop 0
	v_pk_mul_f32 v[100:101], v[110:111], v[98:99]
	v_pk_fma_f32 v[98:99], v[110:111], v[98:99], v[110:111] neg_lo:[1,0,0] neg_hi:[1,0,0]
	s_nop 0
	v_cndmask_b32_e32 v98, v98, v100, vcc
	v_cmp_gt_f32_e32 vcc, 0, v111
	s_nop 1
	v_cndmask_b32_e32 v99, v99, v101, vcc
	v_pk_mul_f32 v[88:89], v[98:99], v[70:71]
	v_pk_mul_f32 v[70:71], v[96:97], v[68:69]
	v_cvt_pk_bf16_f32 v68, v72, v73
	v_mad_i64_i32 v[72:73], s[0:1], v112, s93, v[76:77]
	v_cvt_pk_bf16_f32 v69, v74, v75
	v_cvt_pk_bf16_f32 v70, v70, v71
	v_cvt_pk_bf16_f32 v71, v88, v89
	v_lshl_add_u64 v[72:73], v[72:73], 0, v[78:79]
	global_store_dwordx4 v[72:73], v[68:71], off
	s_nop 1
	v_and_b32_e32 v69, 0x7fffffff, v81
	v_and_b32_e32 v68, 0x7fffffff, v80
	v_pk_fma_f32 v[68:69], v[68:69], s[58:59], 1.0 op_sel_hi:[1,0,0]
	v_pk_mul_f32 v[72:73], v[80:81], v[80:81]
	v_rcp_f32_e32 v68, v68
	v_rcp_f32_e32 v69, v69
	v_pk_mul_f32 v[72:73], v[72:73], s[50:51] op_sel_hi:[1,0]
	v_cmp_gt_f32_e32 vcc, 0, v80
	v_exp_f32_e32 v72, v72
	v_pk_fma_f32 v[70:71], v[68:69], s[60:61], v[128:129] op_sel_hi:[1,0,0]
	v_exp_f32_e32 v73, v73
	v_pk_fma_f32 v[70:71], v[68:69], v[70:71], s[62:63] op_sel_hi:[1,1,0]
	v_add_u32_e32 v88, 48, v179
	v_pk_fma_f32 v[70:71], v[68:69], v[70:71], s[64:65] op_sel_hi:[1,1,0]
	s_nop 0
	v_pk_fma_f32 v[70:71], v[68:69], v[70:71], s[66:67] op_sel_hi:[1,1,0]
	s_nop 0
	v_pk_mul_f32 v[68:69], v[68:69], v[70:71]
	v_pk_mul_f32 v[70:71], v[82:83], v[82:83]
	v_pk_mul_f32 v[68:69], v[72:73], v[68:69]
	v_pk_mul_f32 v[70:71], v[70:71], s[50:51] op_sel_hi:[1,0]
	v_pk_mul_f32 v[72:73], v[80:81], v[68:69]
	v_pk_fma_f32 v[68:69], v[80:81], v[68:69], v[80:81] neg_lo:[1,0,0] neg_hi:[1,0,0]
	v_exp_f32_e32 v70, v70
	v_cndmask_b32_e32 v68, v68, v72, vcc
	v_cmp_gt_f32_e32 vcc, 0, v81
	v_and_b32_e32 v72, 0x7fffffff, v82
	v_exp_f32_e32 v71, v71
	v_cndmask_b32_e32 v69, v69, v73, vcc
	v_and_b32_e32 v73, 0x7fffffff, v83
	v_pk_fma_f32 v[72:73], v[72:73], s[58:59], 1.0 op_sel_hi:[1,0,0]
	v_cmp_gt_f32_e32 vcc, 0, v82
	v_rcp_f32_e32 v72, v72
	v_rcp_f32_e32 v73, v73
	v_pk_mul_f32 v[80:81], v[92:93], v[92:93]
	v_pk_mul_f32 v[68:69], v[68:69], v[84:85]
	v_pk_mul_f32 v[80:81], v[80:81], s[50:51] op_sel_hi:[1,0]
	v_pk_fma_f32 v[74:75], v[72:73], s[60:61], v[128:129] op_sel_hi:[1,0,0]
	v_exp_f32_e32 v80, v80
	v_pk_fma_f32 v[74:75], v[72:73], v[74:75], s[62:63] op_sel_hi:[1,1,0]
	v_exp_f32_e32 v81, v81
	v_pk_fma_f32 v[74:75], v[72:73], v[74:75], s[64:65] op_sel_hi:[1,1,0]
	s_nop 0
	v_pk_fma_f32 v[74:75], v[72:73], v[74:75], s[66:67] op_sel_hi:[1,1,0]
; #define PG8_LAS __attribute__((address_space(3)))
;     __device__ __forceinline__ void operator()(f32x4 (&acc)[2][2][4][2], const Unit& u, int wr, int wc, int fr_, int fq_) const {
;     ...
;         for (int ai = 0; ai < 2; ++ai) {
;             const int blk = 2 * ai + wr;
;             float rsr[4];
; #pragma unroll
;             for (int m = 0; m < 4; ++m) rsr[m] = rsL[blk * 64 + m * 16 + fr];
;             const float rs14 = blk ? rsL[blk * 64 - 2] : 0.f, rs15 = blk ? rsL[blk * 64 - 1] : 0.f;
; #pragma unroll
;             for (int bj = 0; bj < 2; ++bj)
; #pragma unroll
;                 for (int n = 0; n < 2; ++n) {
;                     const int ct = bj * HALF + wc * 32 + 8 * fq + 4 * n;
;                     const int cidx = bj * 5632 + jcol + 4 * n;
;                     const f32x4 w0 = *(const f32x4*)(cw + cidx), w1 = *(const f32x4*)(cw + 11264 + cidx), w2 = *(const f32x4*)(cw + 22528 + cidx), b4 = *(const f32x4*)(cb + cidx);
;                     f32x4 pR1 = (f32x4){0.f, 0.f, 0.f, 0.f}, pR2 = pR1;
;                     if (blk) { const f32x4 h14 = *(const PG8_LAS f32x4*)(hal + ((blk - 1) * 2 + 0) * 256 + ct) * rs14, h15 = *(const PG8_LAS f32x4*)(hal + ((blk - 1) * 2 + 1) * 256 + ct) * rs15;
;                         pR1 = h15; pR2 = (fr == 0) ? h14 : h15; }
; #pragma unroll
;                     for (int m = 0; m < 4; ++m) {
;                         const f32x4 U = acc[ai][bj][m][n] * rsr[m];
;                         f32x4 R1, R2;
; #pragma unroll
;                         for (int i = 0; i < 4; ++i) { R1[i] = dpp_ror1(U[i]); R2[i] = dpp_ror2(U[i]); }
;                         const f32x4 U1 = (fr >= 1) ? R1 : pR1, U2 = (fr >= 2) ? R2 : pR2;
;                         const f32x4 C = b4 + w0 * U2 + w1 * U1 + w2 * U;
;                         acc[ai][bj][m][n] = C; pR1 = R1; pR2 = R2;
;                         asm volatile("" : "+v"(acc[ai][bj][m][n]));
;                         __builtin_amdgcn_sched_barrier(0);
;                     }
;     ...
;             for (int m = 0; m < 4; ++m) { const int row = u.pm * BM + blk * 64 + m * 16 + fr;
;                 const f32x4 g0 = gelu4(acc[ai][0][m][0]), g1 = gelu4(acc[ai][0][m][1]);
;                 *(u32x4*)(ACT + (size_t)row * 5632 + jcol) = pack8(g0 * acc[ai][1][m][0], g1 * acc[ai][1][m][1]); asm volatile("" ::: "memory"); __builtin_amdgcn_sched_barrier(0); }
	s_nop 0
	v_pk_mul_f32 v[72:73], v[72:73], v[74:75]
	s_nop 0
	v_pk_mul_f32 v[70:71], v[70:71], v[72:73]
	s_nop 0
	v_pk_mul_f32 v[72:73], v[82:83], v[70:71]
	v_pk_fma_f32 v[70:71], v[82:83], v[70:71], v[82:83] neg_lo:[1,0,0] neg_hi:[1,0,0]
	s_nop 0
	v_cndmask_b32_e32 v70, v70, v72, vcc
	v_cmp_gt_f32_e32 vcc, 0, v83
	v_and_b32_e32 v72, 0x7fffffff, v92
	s_nop 0
	v_cndmask_b32_e32 v71, v71, v73, vcc
	v_and_b32_e32 v73, 0x7fffffff, v93
	v_pk_fma_f32 v[72:73], v[72:73], s[58:59], 1.0 op_sel_hi:[1,0,0]
	v_cmp_gt_f32_e32 vcc, 0, v92
	v_rcp_f32_e32 v72, v72
	v_rcp_f32_e32 v73, v73
	v_pk_mul_f32 v[70:71], v[70:71], v[86:87]
	v_pk_fma_f32 v[74:75], v[72:73], s[60:61], v[128:129] op_sel_hi:[1,0,0]
	s_nop 0
	v_pk_fma_f32 v[74:75], v[72:73], v[74:75], s[62:63] op_sel_hi:[1,1,0]
	s_nop 0
	v_pk_fma_f32 v[74:75], v[72:73], v[74:75], s[64:65] op_sel_hi:[1,1,0]
	s_nop 0
	v_pk_fma_f32 v[74:75], v[72:73], v[74:75], s[66:67] op_sel_hi:[1,1,0]
	s_nop 0
	v_pk_mul_f32 v[72:73], v[72:73], v[74:75]
	v_pk_mul_f32 v[74:75], v[94:95], v[94:95]
	v_pk_mul_f32 v[72:73], v[80:81], v[72:73]
	v_pk_mul_f32 v[74:75], v[74:75], s[50:51] op_sel_hi:[1,0]
	v_pk_mul_f32 v[80:81], v[92:93], v[72:73]
	v_pk_fma_f32 v[72:73], v[92:93], v[72:73], v[92:93] neg_lo:[1,0,0] neg_hi:[1,0,0]
	v_exp_f32_e32 v74, v74
	v_cndmask_b32_e32 v72, v72, v80, vcc
	v_cmp_gt_f32_e32 vcc, 0, v93
	v_and_b32_e32 v80, 0x7fffffff, v94
	v_exp_f32_e32 v75, v75
	v_cndmask_b32_e32 v73, v73, v81, vcc
	v_and_b32_e32 v81, 0x7fffffff, v95
	v_pk_fma_f32 v[80:81], v[80:81], s[58:59], 1.0 op_sel_hi:[1,0,0]
	v_cmp_gt_f32_e32 vcc, 0, v94
	v_rcp_f32_e32 v80, v80
	v_rcp_f32_e32 v81, v81
	s_nop 0
	v_pk_fma_f32 v[82:83], v[80:81], s[60:61], v[128:129] op_sel_hi:[1,0,0]
	s_nop 0
	v_pk_fma_f32 v[82:83], v[80:81], v[82:83], s[62:63] op_sel_hi:[1,1,0]
	s_nop 0
	v_pk_fma_f32 v[82:83], v[80:81], v[82:83], s[64:65] op_sel_hi:[1,1,0]
	s_nop 0
	v_pk_fma_f32 v[82:83], v[80:81], v[82:83], s[66:67] op_sel_hi:[1,1,0]
	s_nop 0
	v_pk_mul_f32 v[80:81], v[80:81], v[82:83]
	s_nop 0
	v_pk_mul_f32 v[74:75], v[74:75], v[80:81]
	s_nop 0
	v_pk_mul_f32 v[80:81], v[94:95], v[74:75]
	v_pk_fma_f32 v[74:75], v[94:95], v[74:75], v[94:95] neg_lo:[1,0,0] neg_hi:[1,0,0]
	s_nop 0
	v_cndmask_b32_e32 v74, v74, v80, vcc
	v_cmp_gt_f32_e32 vcc, 0, v95
	s_nop 1
	v_cndmask_b32_e32 v75, v75, v81, vcc
	v_pk_mul_f32 v[74:75], v[74:75], v[66:67]
	v_pk_mul_f32 v[66:67], v[72:73], v[64:65]
	v_cvt_pk_bf16_f32 v64, v68, v69
	v_mad_i64_i32 v[68:69], s[0:1], v88, s93, v[76:77]
	v_cvt_pk_bf16_f32 v65, v70, v71
	v_cvt_pk_bf16_f32 v66, v66, v67
	v_cvt_pk_bf16_f32 v67, v74, v75
	v_lshl_add_u64 v[68:69], v[68:69], 0, v[78:79]
	global_store_dwordx4 v[68:69], v[64:67], off
	global_load_dwordx4 v[80:83], v[166:167], off
	global_load_dwordx4 v[84:87], v[164:165], off
	global_load_dwordx4 v[88:91], v[168:169], off
	global_load_dwordx4 v[92:95], v[170:171], off
	v_mov_b32_e32 v65, s96
	v_add_u32_e32 v71, s97, v154
	ds_read_b64 v[66:67], v65
	ds_read_b128 v[96:99], v71
	v_add_u32_e32 v64, s89, v225
	v_add_u32_e32 v73, s14, v154
	ds_read_b128 v[100:103], v73
	ds_read2_b32 v[68:69], v64 offset1:16
	ds_read2_b32 v[64:65], v64 offset0:32 offset1:48
	s_waitcnt lgkmcnt(3)
	v_pk_mul_f32 v[74:75], v[66:67], v[98:99] op_sel_hi:[0,1]
	v_pk_mul_f32 v[96:97], v[66:67], v[96:97] op_sel_hi:[0,1]
	s_waitcnt lgkmcnt(2)
	v_pk_mul_f32 v[98:99], v[66:67], v[102:103] op_sel:[1,0]
	v_pk_mul_f32 v[100:101], v[66:67], v[100:101] op_sel:[1,0]
	v_cndmask_b32_e64 v70, v99, v75, s[10:11]
	v_cndmask_b32_e64 v72, v98, v74, s[10:11]
	v_cndmask_b32_e64 v102, v101, v97, s[10:11]
	v_cndmask_b32_e64 v103, v100, v96, s[10:11]
	s_waitcnt lgkmcnt(1)
	v_pk_mul_f32 v[62:63], v[62:63], v[68:69] op_sel_hi:[1,0]
	v_pk_mul_f32 v[60:61], v[60:61], v[68:69] op_sel_hi:[1,0]
	s_nop 0
	s_nop 1
	v_mov_b32_dpp v104, v60 row_ror:1 row_mask:0xf bank_mask:0xf
	v_mov_b32_dpp v105, v60 row_ror:2 row_mask:0xf bank_mask:0xf
	v_mov_b32_dpp v106, v61 row_ror:1 row_mask:0xf bank_mask:0xf
	v_mov_b32_dpp v107, v61 row_ror:2 row_mask:0xf bank_mask:0xf
	v_mov_b32_dpp v108, v62 row_ror:1 row_mask:0xf bank_mask:0xf
	v_mov_b32_dpp v109, v62 row_ror:2 row_mask:0xf bank_mask:0xf
	v_mov_b32_dpp v110, v63 row_ror:1 row_mask:0xf bank_mask:0xf
	v_mov_b32_dpp v111, v63 row_ror:2 row_mask:0xf bank_mask:0xf
	v_cndmask_b32_e64 v96, v100, v104, s[6:7]
	v_cndmask_b32_e64 v74, v98, v108, s[6:7]
	v_cndmask_b32_e64 v75, v99, v110, s[6:7]
	v_cndmask_b32_e64 v97, v101, v106, s[6:7]
	v_cndmask_b32_e64 v98, v72, v109, s[8:9]
	v_cndmask_b32_e64 v99, v70, v111, s[8:9]
	v_cndmask_b32_e64 v100, v103, v105, s[8:9]
	v_cndmask_b32_e64 v101, v102, v107, s[8:9]
	s_waitcnt vmcnt(2)
	v_pk_fma_f32 v[98:99], v[86:87], v[98:99], v[82:83]
	v_pk_fma_f32 v[100:101], v[84:85], v[100:101], v[80:81]
	s_waitcnt vmcnt(1)
	v_pk_fma_f32 v[74:75], v[90:91], v[74:75], v[98:99]
	v_pk_fma_f32 v[96:97], v[88:89], v[96:97], v[100:101]
	s_waitcnt vmcnt(0)
	v_pk_fma_f32 v[62:63], v[62:63], v[94:95], v[74:75]
	v_pk_fma_f32 v[60:61], v[60:61], v[92:93], v[96:97]
	s_nop 0
	v_mov_b32_e32 v70, v69
	v_pk_mul_f32 v[58:59], v[58:59], v[70:71] op_sel_hi:[1,0]
	v_pk_mul_f32 v[56:57], v[56:57], v[70:71] op_sel_hi:[1,0]
	s_nop 1
	v_mov_b32_dpp v69, v56 row_ror:1 row_mask:0xf bank_mask:0xf
	v_mov_b32_dpp v72, v56 row_ror:2 row_mask:0xf bank_mask:0xf
	v_mov_b32_dpp v102, v57 row_ror:1 row_mask:0xf bank_mask:0xf
	v_mov_b32_dpp v103, v57 row_ror:2 row_mask:0xf bank_mask:0xf
	v_mov_b32_dpp v112, v58 row_ror:1 row_mask:0xf bank_mask:0xf
	v_mov_b32_dpp v113, v58 row_ror:2 row_mask:0xf bank_mask:0xf
	v_mov_b32_dpp v114, v59 row_ror:1 row_mask:0xf bank_mask:0xf
	v_mov_b32_dpp v115, v59 row_ror:2 row_mask:0xf bank_mask:0xf
	v_cndmask_b32_e64 v100, v105, v72, s[8:9]
	v_cndmask_b32_e64 v98, v109, v113, s[8:9]
	v_cndmask_b32_e64 v99, v111, v115, s[8:9]
	v_cndmask_b32_e64 v101, v107, v103, s[8:9]
	v_cndmask_b32_e64 v74, v108, v112, s[6:7]
	v_cndmask_b32_e64 v75, v110, v114, s[6:7]
	v_cndmask_b32_e64 v96, v104, v69, s[6:7]
	v_cndmask_b32_e64 v97, v106, v102, s[6:7]
	v_pk_fma_f32 v[98:99], v[86:87], v[98:99], v[82:83]
	v_pk_fma_f32 v[100:101], v[84:85], v[100:101], v[80:81]
	v_pk_fma_f32 v[74:75], v[90:91], v[74:75], v[98:99]
	v_pk_fma_f32 v[96:97], v[88:89], v[96:97], v[100:101]
	v_pk_fma_f32 v[58:59], v[58:59], v[94:95], v[74:75]
	v_pk_fma_f32 v[56:57], v[56:57], v[92:93], v[96:97]
	s_nop 0
	s_waitcnt lgkmcnt(0)
; #define PG8_LAS __attribute__((address_space(3)))
; __device__ __forceinline__ float dpp_ror1(float x) { float r; asm volatile("s_nop 1\n\tv_mov_b32_dpp %0, %1 row_ror:1 row_mask:0xf bank_mask:0xf" : "=&v"(r) : "v"(x)); return r; }
; __device__ __forceinline__ float dpp_ror2(float x) { float r; asm volatile("s_nop 1\n\tv_mov_b32_dpp %0, %1 row_ror:2 row_mask:0xf bank_mask:0xf" : "=&v"(r) : "v"(x)); return r; }
;     __device__ __forceinline__ void operator()(f32x4 (&acc)[2][2][4][2], const Unit& u, int wr, int wc, int fr_, int fq_) const {
;     ...
;             for (int bj = 0; bj < 2; ++bj)
; #pragma unroll
;                 for (int n = 0; n < 2; ++n) {
;                     const int ct = bj * HALF + wc * 32 + 8 * fq + 4 * n;
;                     const int cidx = bj * 5632 + jcol + 4 * n;
;                     const f32x4 w0 = *(const f32x4*)(cw + cidx), w1 = *(const f32x4*)(cw + 11264 + cidx), w2 = *(const f32x4*)(cw + 22528 + cidx), b4 = *(const f32x4*)(cb + cidx);
;                     f32x4 pR1 = (f32x4){0.f, 0.f, 0.f, 0.f}, pR2 = pR1;
;                     if (blk) { const f32x4 h14 = *(const PG8_LAS f32x4*)(hal + ((blk - 1) * 2 + 0) * 256 + ct) * rs14, h15 = *(const PG8_LAS f32x4*)(hal + ((blk - 1) * 2 + 1) * 256 + ct) * rs15;
;                         pR1 = h15; pR2 = (fr == 0) ? h14 : h15; }
; #pragma unroll
;                     for (int m = 0; m < 4; ++m) {
;                         const f32x4 U = acc[ai][bj][m][n] * rsr[m];
;                         f32x4 R1, R2;
; #pragma unroll
;                         for (int i = 0; i < 4; ++i) { R1[i] = dpp_ror1(U[i]); R2[i] = dpp_ror2(U[i]); }
;                         const f32x4 U1 = (fr >= 1) ? R1 : pR1, U2 = (fr >= 2) ? R2 : pR2;
;                         const f32x4 C = b4 + w0 * U2 + w1 * U1 + w2 * U;
;                         acc[ai][bj][m][n] = C; pR1 = R1; pR2 = R2;
;                         asm volatile("" : "+v"(acc[ai][bj][m][n]));
;                         __builtin_amdgcn_sched_barrier(0);
;                     }
	v_pk_mul_f32 v[54:55], v[54:55], v[64:65] op_sel_hi:[1,0]
	v_pk_mul_f32 v[52:53], v[52:53], v[64:65] op_sel_hi:[1,0]
	s_nop 0
	s_nop 1
	v_mov_b32_dpp v104, v52 row_ror:1 row_mask:0xf bank_mask:0xf
	v_mov_b32_dpp v105, v52 row_ror:2 row_mask:0xf bank_mask:0xf
	v_mov_b32_dpp v106, v53 row_ror:1 row_mask:0xf bank_mask:0xf
	v_mov_b32_dpp v107, v53 row_ror:2 row_mask:0xf bank_mask:0xf
	v_mov_b32_dpp v108, v54 row_ror:1 row_mask:0xf bank_mask:0xf
	v_mov_b32_dpp v109, v54 row_ror:2 row_mask:0xf bank_mask:0xf
	v_mov_b32_dpp v110, v55 row_ror:1 row_mask:0xf bank_mask:0xf
	v_mov_b32_dpp v111, v55 row_ror:2 row_mask:0xf bank_mask:0xf
	v_cndmask_b32_e64 v100, v72, v105, s[8:9]
	v_cndmask_b32_e64 v98, v113, v109, s[8:9]
	v_cndmask_b32_e64 v99, v115, v111, s[8:9]
	v_cndmask_b32_e64 v101, v103, v107, s[8:9]
	v_cndmask_b32_e64 v74, v112, v108, s[6:7]
	v_cndmask_b32_e64 v75, v114, v110, s[6:7]
	v_cndmask_b32_e64 v96, v69, v104, s[6:7]
	v_cndmask_b32_e64 v97, v102, v106, s[6:7]
	v_pk_fma_f32 v[98:99], v[86:87], v[98:99], v[82:83]
	v_pk_fma_f32 v[100:101], v[84:85], v[100:101], v[80:81]
	v_pk_fma_f32 v[74:75], v[90:91], v[74:75], v[98:99]
	v_pk_fma_f32 v[96:97], v[88:89], v[96:97], v[100:101]
	v_pk_fma_f32 v[54:55], v[54:55], v[94:95], v[74:75]
	v_pk_fma_f32 v[52:53], v[52:53], v[92:93], v[96:97]
	v_mov_b32_e32 v72, v65
	v_pk_mul_f32 v[50:51], v[50:51], v[72:73] op_sel_hi:[1,0]
	v_pk_mul_f32 v[48:49], v[48:49], v[72:73] op_sel_hi:[1,0]
	s_nop 1
	v_mov_b32_dpp v65, v48 row_ror:1 row_mask:0xf bank_mask:0xf
	v_mov_b32_dpp v69, v48 row_ror:2 row_mask:0xf bank_mask:0xf
	v_mov_b32_dpp v97, v49 row_ror:1 row_mask:0xf bank_mask:0xf
	v_mov_b32_dpp v101, v49 row_ror:2 row_mask:0xf bank_mask:0xf
	v_mov_b32_dpp v74, v50 row_ror:1 row_mask:0xf bank_mask:0xf
	v_mov_b32_dpp v98, v50 row_ror:2 row_mask:0xf bank_mask:0xf
	v_mov_b32_dpp v75, v51 row_ror:1 row_mask:0xf bank_mask:0xf
	v_mov_b32_dpp v99, v51 row_ror:2 row_mask:0xf bank_mask:0xf
	v_cndmask_b32_e64 v100, v105, v69, s[8:9]
	v_cndmask_b32_e64 v98, v109, v98, s[8:9]
	v_cndmask_b32_e64 v99, v111, v99, s[8:9]
	v_cndmask_b32_e64 v101, v107, v101, s[8:9]
	v_cndmask_b32_e64 v74, v108, v74, s[6:7]
	v_cndmask_b32_e64 v75, v110, v75, s[6:7]
	v_cndmask_b32_e64 v96, v104, v65, s[6:7]
	v_cndmask_b32_e64 v97, v106, v97, s[6:7]
	v_pk_fma_f32 v[82:83], v[86:87], v[98:99], v[82:83]
	v_pk_fma_f32 v[80:81], v[84:85], v[100:101], v[80:81]
	v_pk_fma_f32 v[74:75], v[90:91], v[74:75], v[82:83]
	v_pk_fma_f32 v[80:81], v[88:89], v[96:97], v[80:81]
	v_pk_fma_f32 v[50:51], v[50:51], v[94:95], v[74:75]
	v_pk_fma_f32 v[48:49], v[48:49], v[92:93], v[80:81]
	s_nop 0
	global_load_dwordx4 v[80:83], v[164:165], off offset:16
	global_load_dwordx4 v[84:87], v[166:167], off offset:16
	global_load_dwordx4 v[88:91], v[172:173], off
	global_load_dwordx4 v[92:95], v[174:175], off
	v_pk_mul_f32 v[74:75], v[46:47], v[68:69] op_sel_hi:[1,0]
	v_pk_mul_f32 v[100:101], v[44:45], v[68:69] op_sel_hi:[1,0]
	ds_read_b128 v[44:47], v71 offset:16
	ds_read_b128 v[96:99], v73 offset:16
	s_nop 1
	v_mov_b32_dpp v65, v100 row_ror:1 row_mask:0xf bank_mask:0xf
	v_mov_b32_dpp v69, v100 row_ror:2 row_mask:0xf bank_mask:0xf
	v_mov_b32_dpp v102, v101 row_ror:1 row_mask:0xf bank_mask:0xf
	s_waitcnt lgkmcnt(1)
	v_pk_mul_f32 v[46:47], v[66:67], v[46:47] op_sel_hi:[0,1]
	v_pk_mul_f32 v[44:45], v[66:67], v[44:45] op_sel_hi:[0,1]
	s_waitcnt lgkmcnt(0)
	v_pk_mul_f32 v[98:99], v[66:67], v[98:99] op_sel:[1,0]
	v_pk_mul_f32 v[96:97], v[66:67], v[96:97] op_sel:[1,0]
	v_cndmask_b32_e64 v108, v99, v47, s[10:11]
	v_cndmask_b32_e64 v109, v98, v46, s[10:11]
	v_cndmask_b32_e64 v110, v96, v44, s[10:11]
	v_cndmask_b32_e64 v111, v97, v45, s[10:11]
	s_nop 1
	v_mov_b32_dpp v103, v101 row_ror:2 row_mask:0xf bank_mask:0xf
	v_mov_b32_dpp v104, v74 row_ror:1 row_mask:0xf bank_mask:0xf
	v_mov_b32_dpp v105, v74 row_ror:2 row_mask:0xf bank_mask:0xf
	v_mov_b32_dpp v106, v75 row_ror:1 row_mask:0xf bank_mask:0xf
	v_mov_b32_dpp v107, v75 row_ror:2 row_mask:0xf bank_mask:0xf
	v_cndmask_b32_e64 v47, v97, v102, s[6:7]
	v_cndmask_b32_e64 v44, v98, v104, s[6:7]
	v_cndmask_b32_e64 v45, v99, v106, s[6:7]
	v_cndmask_b32_e64 v46, v96, v65, s[6:7]
	v_cndmask_b32_e64 v96, v109, v105, s[8:9]
	v_cndmask_b32_e64 v97, v108, v107, s[8:9]
	v_cndmask_b32_e64 v99, v111, v103, s[8:9]
	v_cndmask_b32_e64 v98, v110, v69, s[8:9]
	s_waitcnt vmcnt(2)
	v_pk_fma_f32 v[96:97], v[82:83], v[96:97], v[86:87]
	v_pk_fma_f32 v[98:99], v[80:81], v[98:99], v[84:85]
	s_waitcnt vmcnt(1)
	v_pk_fma_f32 v[44:45], v[90:91], v[44:45], v[96:97]
	v_pk_fma_f32 v[96:97], v[88:89], v[46:47], v[98:99]
	s_waitcnt vmcnt(0)
; #define PG8_LAS __attribute__((address_space(3)))
; __device__ __forceinline__ float dpp_ror1(float x) { float r; asm volatile("s_nop 1\n\tv_mov_b32_dpp %0, %1 row_ror:1 row_mask:0xf bank_mask:0xf" : "=&v"(r) : "v"(x)); return r; }
; __device__ __forceinline__ float dpp_ror2(float x) { float r; asm volatile("s_nop 1\n\tv_mov_b32_dpp %0, %1 row_ror:2 row_mask:0xf bank_mask:0xf" : "=&v"(r) : "v"(x)); return r; }
;     __device__ __forceinline__ void operator()(f32x4 (&acc)[2][2][4][2], const Unit& u, int wr, int wc, int fr_, int fq_) const {
;     ...
;             for (int bj = 0; bj < 2; ++bj)
; #pragma unroll
;                 for (int n = 0; n < 2; ++n) {
;                     const int ct = bj * HALF + wc * 32 + 8 * fq + 4 * n;
;                     const int cidx = bj * 5632 + jcol + 4 * n;
;                     const f32x4 w0 = *(const f32x4*)(cw + cidx), w1 = *(const f32x4*)(cw + 11264 + cidx), w2 = *(const f32x4*)(cw + 22528 + cidx), b4 = *(const f32x4*)(cb + cidx);
;                     f32x4 pR1 = (f32x4){0.f, 0.f, 0.f, 0.f}, pR2 = pR1;
;                     if (blk) { const f32x4 h14 = *(const PG8_LAS f32x4*)(hal + ((blk - 1) * 2 + 0) * 256 + ct) * rs14, h15 = *(const PG8_LAS f32x4*)(hal + ((blk - 1) * 2 + 1) * 256 + ct) * rs15;
;                         pR1 = h15; pR2 = (fr == 0) ? h14 : h15; }
; #pragma unroll
;                     for (int m = 0; m < 4; ++m) {
;                         const f32x4 U = acc[ai][bj][m][n] * rsr[m];
;                         f32x4 R1, R2;
; #pragma unroll
;                         for (int i = 0; i < 4; ++i) { R1[i] = dpp_ror1(U[i]); R2[i] = dpp_ror2(U[i]); }
;                         const f32x4 U1 = (fr >= 1) ? R1 : pR1, U2 = (fr >= 2) ? R2 : pR2;
;                         const f32x4 C = b4 + w0 * U2 + w1 * U1 + w2 * U;
;                         acc[ai][bj][m][n] = C; pR1 = R1; pR2 = R2;
;                         asm volatile("" : "+v"(acc[ai][bj][m][n]));
;                         __builtin_amdgcn_sched_barrier(0);
;                     }
	v_pk_fma_f32 v[46:47], v[74:75], v[94:95], v[44:45]
	v_pk_fma_f32 v[44:45], v[100:101], v[92:93], v[96:97]
	s_nop 0
	v_pk_mul_f32 v[42:43], v[42:43], v[70:71] op_sel_hi:[1,0]
	v_pk_mul_f32 v[40:41], v[40:41], v[70:71] op_sel_hi:[1,0]
	s_nop 1
	v_mov_b32_dpp v108, v40 row_ror:1 row_mask:0xf bank_mask:0xf
	v_mov_b32_dpp v109, v40 row_ror:2 row_mask:0xf bank_mask:0xf
	v_mov_b32_dpp v110, v41 row_ror:1 row_mask:0xf bank_mask:0xf
	v_mov_b32_dpp v111, v41 row_ror:2 row_mask:0xf bank_mask:0xf
	v_mov_b32_dpp v112, v42 row_ror:1 row_mask:0xf bank_mask:0xf
	v_mov_b32_dpp v113, v42 row_ror:2 row_mask:0xf bank_mask:0xf
	v_mov_b32_dpp v114, v43 row_ror:1 row_mask:0xf bank_mask:0xf
	v_mov_b32_dpp v115, v43 row_ror:2 row_mask:0xf bank_mask:0xf
	v_cndmask_b32_e64 v100, v69, v109, s[8:9]
	v_cndmask_b32_e64 v98, v105, v113, s[8:9]
	v_cndmask_b32_e64 v99, v107, v115, s[8:9]
	v_cndmask_b32_e64 v101, v103, v111, s[8:9]
	v_cndmask_b32_e64 v74, v104, v112, s[6:7]
	v_cndmask_b32_e64 v75, v106, v114, s[6:7]
	v_cndmask_b32_e64 v96, v65, v108, s[6:7]
	v_cndmask_b32_e64 v97, v102, v110, s[6:7]
	v_pk_fma_f32 v[98:99], v[82:83], v[98:99], v[86:87]
	v_pk_fma_f32 v[100:101], v[80:81], v[100:101], v[84:85]
	v_pk_fma_f32 v[74:75], v[90:91], v[74:75], v[98:99]
	v_pk_fma_f32 v[96:97], v[88:89], v[96:97], v[100:101]
	v_pk_fma_f32 v[42:43], v[42:43], v[94:95], v[74:75]
	v_pk_fma_f32 v[40:41], v[40:41], v[92:93], v[96:97]
	v_pk_mul_f32 v[38:39], v[38:39], v[64:65] op_sel_hi:[1,0]
	v_pk_mul_f32 v[36:37], v[36:37], v[64:65] op_sel_hi:[1,0]
	s_nop 1
	v_mov_b32_dpp v65, v36 row_ror:1 row_mask:0xf bank_mask:0xf
	v_mov_b32_dpp v69, v36 row_ror:2 row_mask:0xf bank_mask:0xf
	v_mov_b32_dpp v102, v37 row_ror:1 row_mask:0xf bank_mask:0xf
	v_mov_b32_dpp v103, v37 row_ror:2 row_mask:0xf bank_mask:0xf
	v_mov_b32_dpp v104, v38 row_ror:1 row_mask:0xf bank_mask:0xf
	v_mov_b32_dpp v105, v38 row_ror:2 row_mask:0xf bank_mask:0xf
	v_mov_b32_dpp v106, v39 row_ror:1 row_mask:0xf bank_mask:0xf
	v_mov_b32_dpp v107, v39 row_ror:2 row_mask:0xf bank_mask:0xf
	v_cndmask_b32_e64 v100, v109, v69, s[8:9]
	v_cndmask_b32_e64 v98, v113, v105, s[8:9]
	v_cndmask_b32_e64 v99, v115, v107, s[8:9]
	v_cndmask_b32_e64 v101, v111, v103, s[8:9]
	v_cndmask_b32_e64 v74, v112, v104, s[6:7]
	v_cndmask_b32_e64 v75, v114, v106, s[6:7]
	v_cndmask_b32_e64 v96, v108, v65, s[6:7]
	v_cndmask_b32_e64 v97, v110, v102, s[6:7]
	v_pk_fma_f32 v[98:99], v[82:83], v[98:99], v[86:87]
	v_pk_fma_f32 v[100:101], v[80:81], v[100:101], v[84:85]
	v_pk_fma_f32 v[74:75], v[90:91], v[74:75], v[98:99]
	v_pk_fma_f32 v[96:97], v[88:89], v[96:97], v[100:101]
	v_pk_fma_f32 v[38:39], v[38:39], v[94:95], v[74:75]
	v_pk_fma_f32 v[36:37], v[36:37], v[92:93], v[96:97]
	v_pk_mul_f32 v[34:35], v[34:35], v[72:73] op_sel_hi:[1,0]
	v_pk_mul_f32 v[32:33], v[32:33], v[72:73] op_sel_hi:[1,0]
	s_nop 1
	v_mov_b32_dpp v96, v32 row_ror:1 row_mask:0xf bank_mask:0xf
	v_mov_b32_dpp v100, v32 row_ror:2 row_mask:0xf bank_mask:0xf
	v_mov_b32_dpp v97, v33 row_ror:1 row_mask:0xf bank_mask:0xf
	v_mov_b32_dpp v101, v33 row_ror:2 row_mask:0xf bank_mask:0xf
	v_mov_b32_dpp v74, v34 row_ror:1 row_mask:0xf bank_mask:0xf
	v_mov_b32_dpp v98, v34 row_ror:2 row_mask:0xf bank_mask:0xf
	v_mov_b32_dpp v75, v35 row_ror:1 row_mask:0xf bank_mask:0xf
	v_mov_b32_dpp v99, v35 row_ror:2 row_mask:0xf bank_mask:0xf
	v_cndmask_b32_e64 v100, v69, v100, s[8:9]
	v_cndmask_b32_e64 v98, v105, v98, s[8:9]
	v_cndmask_b32_e64 v99, v107, v99, s[8:9]
	v_cndmask_b32_e64 v101, v103, v101, s[8:9]
	v_cndmask_b32_e64 v74, v104, v74, s[6:7]
	v_cndmask_b32_e64 v75, v106, v75, s[6:7]
	v_cndmask_b32_e64 v96, v65, v96, s[6:7]
	v_cndmask_b32_e64 v97, v102, v97, s[6:7]
	v_pk_fma_f32 v[82:83], v[82:83], v[98:99], v[86:87]
	v_pk_fma_f32 v[80:81], v[80:81], v[100:101], v[84:85]
	v_pk_fma_f32 v[74:75], v[90:91], v[74:75], v[82:83]
	v_pk_fma_f32 v[80:81], v[88:89], v[96:97], v[80:81]
	v_pk_fma_f32 v[34:35], v[34:35], v[94:95], v[74:75]
	v_pk_fma_f32 v[32:33], v[32:33], v[92:93], v[80:81]
	s_nop 0
	global_load_dwordx4 v[80:83], v[176:177], off
	global_load_dwordx4 v[84:87], v[138:139], off
	global_load_dwordx4 v[88:91], v[140:141], off
	global_load_dwordx4 v[92:95], v[142:143], off
	v_pk_mul_f32 v[74:75], v[30:31], v[68:69] op_sel_hi:[1,0]
	v_pk_mul_f32 v[100:101], v[28:29], v[68:69] op_sel_hi:[1,0]
	ds_read_b128 v[28:31], v71 offset:512
	ds_read_b128 v[96:99], v73 offset:512
	s_nop 1
	v_mov_b32_dpp v65, v100 row_ror:1 row_mask:0xf bank_mask:0xf
	v_mov_b32_dpp v69, v100 row_ror:2 row_mask:0xf bank_mask:0xf
	v_mov_b32_dpp v102, v101 row_ror:1 row_mask:0xf bank_mask:0xf
	s_waitcnt lgkmcnt(1)
	v_pk_mul_f32 v[30:31], v[66:67], v[30:31] op_sel_hi:[0,1]
	v_pk_mul_f32 v[28:29], v[66:67], v[28:29] op_sel_hi:[0,1]
	s_waitcnt lgkmcnt(0)
	v_pk_mul_f32 v[98:99], v[66:67], v[98:99] op_sel:[1,0]
	v_pk_mul_f32 v[96:97], v[66:67], v[96:97] op_sel:[1,0]
	v_cndmask_b32_e64 v108, v99, v31, s[10:11]
	v_cndmask_b32_e64 v109, v98, v30, s[10:11]
	v_cndmask_b32_e64 v110, v96, v28, s[10:11]
	v_cndmask_b32_e64 v111, v97, v29, s[10:11]
	s_nop 1
	v_mov_b32_dpp v103, v101 row_ror:2 row_mask:0xf bank_mask:0xf
	v_mov_b32_dpp v104, v74 row_ror:1 row_mask:0xf bank_mask:0xf
	v_mov_b32_dpp v105, v74 row_ror:2 row_mask:0xf bank_mask:0xf
	v_mov_b32_dpp v106, v75 row_ror:1 row_mask:0xf bank_mask:0xf
	v_mov_b32_dpp v107, v75 row_ror:2 row_mask:0xf bank_mask:0xf
	v_cndmask_b32_e64 v31, v97, v102, s[6:7]
	v_cndmask_b32_e64 v28, v98, v104, s[6:7]
	v_cndmask_b32_e64 v29, v99, v106, s[6:7]
	v_cndmask_b32_e64 v30, v96, v65, s[6:7]
	v_cndmask_b32_e64 v96, v109, v105, s[8:9]
	v_cndmask_b32_e64 v97, v108, v107, s[8:9]
	v_cndmask_b32_e64 v99, v111, v103, s[8:9]
	v_cndmask_b32_e64 v98, v110, v69, s[8:9]
	s_waitcnt vmcnt(2)
; #define PG8_LAS __attribute__((address_space(3)))
; __device__ __forceinline__ float dpp_ror1(float x) { float r; asm volatile("s_nop 1\n\tv_mov_b32_dpp %0, %1 row_ror:1 row_mask:0xf bank_mask:0xf" : "=&v"(r) : "v"(x)); return r; }
; __device__ __forceinline__ float dpp_ror2(float x) { float r; asm volatile("s_nop 1\n\tv_mov_b32_dpp %0, %1 row_ror:2 row_mask:0xf bank_mask:0xf" : "=&v"(r) : "v"(x)); return r; }
;     __device__ __forceinline__ void operator()(f32x4 (&acc)[2][2][4][2], const Unit& u, int wr, int wc, int fr_, int fq_) const {
;     ...
;             for (int bj = 0; bj < 2; ++bj)
; #pragma unroll
;                 for (int n = 0; n < 2; ++n) {
;                     const int ct = bj * HALF + wc * 32 + 8 * fq + 4 * n;
;                     const int cidx = bj * 5632 + jcol + 4 * n;
;                     const f32x4 w0 = *(const f32x4*)(cw + cidx), w1 = *(const f32x4*)(cw + 11264 + cidx), w2 = *(const f32x4*)(cw + 22528 + cidx), b4 = *(const f32x4*)(cb + cidx);
;                     f32x4 pR1 = (f32x4){0.f, 0.f, 0.f, 0.f}, pR2 = pR1;
;                     if (blk) { const f32x4 h14 = *(const PG8_LAS f32x4*)(hal + ((blk - 1) * 2 + 0) * 256 + ct) * rs14, h15 = *(const PG8_LAS f32x4*)(hal + ((blk - 1) * 2 + 1) * 256 + ct) * rs15;
;                         pR1 = h15; pR2 = (fr == 0) ? h14 : h15; }
; #pragma unroll
;                     for (int m = 0; m < 4; ++m) {
;                         const f32x4 U = acc[ai][bj][m][n] * rsr[m];
;                         f32x4 R1, R2;
; #pragma unroll
;                         for (int i = 0; i < 4; ++i) { R1[i] = dpp_ror1(U[i]); R2[i] = dpp_ror2(U[i]); }
;                         const f32x4 U1 = (fr >= 1) ? R1 : pR1, U2 = (fr >= 2) ? R2 : pR2;
;                         const f32x4 C = b4 + w0 * U2 + w1 * U1 + w2 * U;
;                         acc[ai][bj][m][n] = C; pR1 = R1; pR2 = R2;
;                         asm volatile("" : "+v"(acc[ai][bj][m][n]));
;                         __builtin_amdgcn_sched_barrier(0);
;                     }
	v_pk_fma_f32 v[96:97], v[86:87], v[96:97], v[82:83]
	v_pk_fma_f32 v[98:99], v[84:85], v[98:99], v[80:81]
	s_waitcnt vmcnt(1)
	v_pk_fma_f32 v[28:29], v[90:91], v[28:29], v[96:97]
	v_pk_fma_f32 v[96:97], v[88:89], v[30:31], v[98:99]
	s_waitcnt vmcnt(0)
	v_pk_fma_f32 v[30:31], v[74:75], v[94:95], v[28:29]
	v_pk_fma_f32 v[28:29], v[100:101], v[92:93], v[96:97]
	s_nop 0
	v_pk_mul_f32 v[26:27], v[26:27], v[70:71] op_sel_hi:[1,0]
	v_pk_mul_f32 v[24:25], v[24:25], v[70:71] op_sel_hi:[1,0]
	s_nop 1
	v_mov_b32_dpp v108, v24 row_ror:1 row_mask:0xf bank_mask:0xf
	v_mov_b32_dpp v109, v24 row_ror:2 row_mask:0xf bank_mask:0xf
	v_mov_b32_dpp v110, v25 row_ror:1 row_mask:0xf bank_mask:0xf
	v_mov_b32_dpp v111, v25 row_ror:2 row_mask:0xf bank_mask:0xf
	v_mov_b32_dpp v112, v26 row_ror:1 row_mask:0xf bank_mask:0xf
	v_mov_b32_dpp v113, v26 row_ror:2 row_mask:0xf bank_mask:0xf
	v_mov_b32_dpp v114, v27 row_ror:1 row_mask:0xf bank_mask:0xf
	v_mov_b32_dpp v115, v27 row_ror:2 row_mask:0xf bank_mask:0xf
	v_cndmask_b32_e64 v100, v69, v109, s[8:9]
	v_cndmask_b32_e64 v98, v105, v113, s[8:9]
	v_cndmask_b32_e64 v99, v107, v115, s[8:9]
	v_cndmask_b32_e64 v101, v103, v111, s[8:9]
	v_cndmask_b32_e64 v74, v104, v112, s[6:7]
	v_cndmask_b32_e64 v75, v106, v114, s[6:7]
	v_cndmask_b32_e64 v96, v65, v108, s[6:7]
	v_cndmask_b32_e64 v97, v102, v110, s[6:7]
	v_pk_fma_f32 v[98:99], v[86:87], v[98:99], v[82:83]
	v_pk_fma_f32 v[100:101], v[84:85], v[100:101], v[80:81]
	v_pk_fma_f32 v[74:75], v[90:91], v[74:75], v[98:99]
	v_pk_fma_f32 v[96:97], v[88:89], v[96:97], v[100:101]
	v_pk_fma_f32 v[26:27], v[26:27], v[94:95], v[74:75]
	v_pk_fma_f32 v[24:25], v[24:25], v[92:93], v[96:97]
	v_pk_mul_f32 v[22:23], v[22:23], v[64:65] op_sel_hi:[1,0]
	v_pk_mul_f32 v[20:21], v[20:21], v[64:65] op_sel_hi:[1,0]
	s_nop 1
	v_mov_b32_dpp v65, v20 row_ror:1 row_mask:0xf bank_mask:0xf
	v_mov_b32_dpp v69, v20 row_ror:2 row_mask:0xf bank_mask:0xf
	v_mov_b32_dpp v102, v21 row_ror:1 row_mask:0xf bank_mask:0xf
	v_mov_b32_dpp v103, v21 row_ror:2 row_mask:0xf bank_mask:0xf
	v_mov_b32_dpp v104, v22 row_ror:1 row_mask:0xf bank_mask:0xf
	v_mov_b32_dpp v105, v22 row_ror:2 row_mask:0xf bank_mask:0xf
	v_mov_b32_dpp v106, v23 row_ror:1 row_mask:0xf bank_mask:0xf
	v_mov_b32_dpp v107, v23 row_ror:2 row_mask:0xf bank_mask:0xf
	v_cndmask_b32_e64 v100, v109, v69, s[8:9]
	v_cndmask_b32_e64 v98, v113, v105, s[8:9]
	v_cndmask_b32_e64 v99, v115, v107, s[8:9]
	v_cndmask_b32_e64 v101, v111, v103, s[8:9]
	v_cndmask_b32_e64 v74, v112, v104, s[6:7]
	v_cndmask_b32_e64 v75, v114, v106, s[6:7]
	v_cndmask_b32_e64 v96, v108, v65, s[6:7]
	v_cndmask_b32_e64 v97, v110, v102, s[6:7]
	v_pk_fma_f32 v[98:99], v[86:87], v[98:99], v[82:83]
	v_pk_fma_f32 v[100:101], v[84:85], v[100:101], v[80:81]
	v_pk_fma_f32 v[74:75], v[90:91], v[74:75], v[98:99]
	v_pk_fma_f32 v[96:97], v[88:89], v[96:97], v[100:101]
	v_pk_fma_f32 v[22:23], v[22:23], v[94:95], v[74:75]
	v_pk_fma_f32 v[20:21], v[20:21], v[92:93], v[96:97]
	v_pk_mul_f32 v[18:19], v[18:19], v[72:73] op_sel_hi:[1,0]
	v_pk_mul_f32 v[16:17], v[16:17], v[72:73] op_sel_hi:[1,0]
	s_nop 1
	v_mov_b32_dpp v96, v16 row_ror:1 row_mask:0xf bank_mask:0xf
	v_mov_b32_dpp v100, v16 row_ror:2 row_mask:0xf bank_mask:0xf
	v_mov_b32_dpp v97, v17 row_ror:1 row_mask:0xf bank_mask:0xf
	v_mov_b32_dpp v101, v17 row_ror:2 row_mask:0xf bank_mask:0xf
	v_mov_b32_dpp v74, v18 row_ror:1 row_mask:0xf bank_mask:0xf
	v_mov_b32_dpp v98, v18 row_ror:2 row_mask:0xf bank_mask:0xf
	v_mov_b32_dpp v75, v19 row_ror:1 row_mask:0xf bank_mask:0xf
	v_mov_b32_dpp v99, v19 row_ror:2 row_mask:0xf bank_mask:0xf
	v_cndmask_b32_e64 v100, v69, v100, s[8:9]
	v_cndmask_b32_e64 v98, v105, v98, s[8:9]
	v_cndmask_b32_e64 v99, v107, v99, s[8:9]
	v_cndmask_b32_e64 v101, v103, v101, s[8:9]
	v_cndmask_b32_e64 v74, v104, v74, s[6:7]
	v_cndmask_b32_e64 v75, v106, v75, s[6:7]
	v_cndmask_b32_e64 v96, v65, v96, s[6:7]
	v_cndmask_b32_e64 v97, v102, v97, s[6:7]
	v_pk_fma_f32 v[82:83], v[86:87], v[98:99], v[82:83]
	v_pk_fma_f32 v[80:81], v[84:85], v[100:101], v[80:81]
	v_pk_fma_f32 v[74:75], v[90:91], v[74:75], v[82:83]
	v_pk_fma_f32 v[80:81], v[88:89], v[96:97], v[80:81]
	v_pk_fma_f32 v[18:19], v[18:19], v[94:95], v[74:75]
	v_pk_fma_f32 v[16:17], v[16:17], v[92:93], v[80:81]
	s_nop 0
	global_load_dwordx4 v[80:83], v[136:137], off
	global_load_dwordx4 v[84:87], v[130:131], off
	global_load_dwordx4 v[88:91], v[132:133], off
	global_load_dwordx4 v[92:95], v[134:135], off
	v_pk_mul_f32 v[74:75], v[14:15], v[68:69] op_sel_hi:[1,0]
	v_pk_mul_f32 v[68:69], v[12:13], v[68:69] op_sel_hi:[1,0]
	ds_read_b128 v[12:15], v71 offset:528
	ds_read_b128 v[96:99], v73 offset:528
	s_nop 1
	v_mov_b32_dpp v65, v68 row_ror:1 row_mask:0xf bank_mask:0xf
	v_mov_b32_dpp v73, v68 row_ror:2 row_mask:0xf bank_mask:0xf
	v_mov_b32_dpp v71, v69 row_ror:1 row_mask:0xf bank_mask:0xf
	s_waitcnt lgkmcnt(1)
	v_pk_mul_f32 v[14:15], v[66:67], v[14:15] op_sel_hi:[0,1]
	v_pk_mul_f32 v[12:13], v[66:67], v[12:13] op_sel_hi:[0,1]
	s_waitcnt lgkmcnt(0)
	v_pk_mul_f32 v[98:99], v[66:67], v[98:99] op_sel:[1,0]
	v_pk_mul_f32 v[66:67], v[66:67], v[96:97] op_sel:[1,0]
	v_cndmask_b32_e64 v96, v99, v15, s[10:11]
	v_cndmask_b32_e64 v97, v98, v14, s[10:11]
	v_cndmask_b32_e64 v105, v66, v12, s[10:11]
	v_cndmask_b32_e64 v106, v67, v13, s[10:11]
	s_nop 1
	v_mov_b32_dpp v100, v69 row_ror:2 row_mask:0xf bank_mask:0xf
	v_mov_b32_dpp v101, v74 row_ror:1 row_mask:0xf bank_mask:0xf
	v_mov_b32_dpp v102, v74 row_ror:2 row_mask:0xf bank_mask:0xf
	v_mov_b32_dpp v103, v75 row_ror:1 row_mask:0xf bank_mask:0xf
	v_mov_b32_dpp v104, v75 row_ror:2 row_mask:0xf bank_mask:0xf
	v_cndmask_b32_e64 v15, v67, v71, s[6:7]
	v_cndmask_b32_e64 v14, v66, v65, s[6:7]
	v_cndmask_b32_e64 v66, v97, v102, s[8:9]
	v_cndmask_b32_e64 v67, v96, v104, s[8:9]
	v_cndmask_b32_e64 v97, v106, v100, s[8:9]
	v_cndmask_b32_e64 v96, v105, v73, s[8:9]
	v_cndmask_b32_e64 v12, v98, v101, s[6:7]
	v_cndmask_b32_e64 v13, v99, v103, s[6:7]
	s_waitcnt vmcnt(2)
; #define PG8_LAS __attribute__((address_space(3)))
; __device__ __forceinline__ u32x4 pack8(f32x4 v0, f32x4 v1) { u32x4 w; w.x = cvt_pk_bf16(v0[0], v0[1]); w.y = cvt_pk_bf16(v0[2], v0[3]); w.z = cvt_pk_bf16(v1[0], v1[1]); w.w = cvt_pk_bf16(v1[2], v1[3]); return w; }
; __device__ __forceinline__ f32x4 gelu4(f32x4 v) { f32x2 a = gelu_pk((f32x2){v[0], v[1]}), b = gelu_pk((f32x2){v[2], v[3]}); return (f32x4){a.x, a.y, b.x, b.y}; }
;     __device__ __forceinline__ void operator()(f32x4 (&acc)[2][2][4][2], const Unit& u, int wr, int wc, int fr_, int fq_) const {
;     ...
;             for (int bj = 0; bj < 2; ++bj)
; #pragma unroll
;                 for (int n = 0; n < 2; ++n) {
;                     const int ct = bj * HALF + wc * 32 + 8 * fq + 4 * n;
;                     const int cidx = bj * 5632 + jcol + 4 * n;
;                     const f32x4 w0 = *(const f32x4*)(cw + cidx), w1 = *(const f32x4*)(cw + 11264 + cidx), w2 = *(const f32x4*)(cw + 22528 + cidx), b4 = *(const f32x4*)(cb + cidx);
;                     f32x4 pR1 = (f32x4){0.f, 0.f, 0.f, 0.f}, pR2 = pR1;
;                     if (blk) { const f32x4 h14 = *(const PG8_LAS f32x4*)(hal + ((blk - 1) * 2 + 0) * 256 + ct) * rs14, h15 = *(const PG8_LAS f32x4*)(hal + ((blk - 1) * 2 + 1) * 256 + ct) * rs15;
;                         pR1 = h15; pR2 = (fr == 0) ? h14 : h15; }
; #pragma unroll
;                     for (int m = 0; m < 4; ++m) {
;                         const f32x4 U = acc[ai][bj][m][n] * rsr[m];
;                         f32x4 R1, R2;
; #pragma unroll
;                         for (int i = 0; i < 4; ++i) { R1[i] = dpp_ror1(U[i]); R2[i] = dpp_ror2(U[i]); }
;                         const f32x4 U1 = (fr >= 1) ? R1 : pR1, U2 = (fr >= 2) ? R2 : pR2;
;                         const f32x4 C = b4 + w0 * U2 + w1 * U1 + w2 * U;
;                         acc[ai][bj][m][n] = C; pR1 = R1; pR2 = R2;
;                         asm volatile("" : "+v"(acc[ai][bj][m][n]));
;                         __builtin_amdgcn_sched_barrier(0);
;                     }
;     ...
;             for (int m = 0; m < 4; ++m) { const int row = u.pm * BM + blk * 64 + m * 16 + fr;
;                 const f32x4 g0 = gelu4(acc[ai][0][m][0]), g1 = gelu4(acc[ai][0][m][1]);
;                 *(u32x4*)(ACT + (size_t)row * 5632 + jcol) = pack8(g0 * acc[ai][1][m][0], g1 * acc[ai][1][m][1]); asm volatile("" ::: "memory"); __builtin_amdgcn_sched_barrier(0); }
	v_pk_fma_f32 v[66:67], v[86:87], v[66:67], v[82:83]
	v_pk_fma_f32 v[96:97], v[84:85], v[96:97], v[80:81]
	s_waitcnt vmcnt(1)
	v_pk_fma_f32 v[12:13], v[90:91], v[12:13], v[66:67]
	v_pk_fma_f32 v[66:67], v[88:89], v[14:15], v[96:97]
	s_waitcnt vmcnt(0)
	v_pk_fma_f32 v[14:15], v[74:75], v[94:95], v[12:13]
	v_pk_fma_f32 v[12:13], v[68:69], v[92:93], v[66:67]
	s_nop 0
	v_pk_mul_f32 v[10:11], v[10:11], v[70:71] op_sel_hi:[1,0]
	v_pk_mul_f32 v[8:9], v[8:9], v[70:71] op_sel_hi:[1,0]
	s_nop 1
	v_mov_b32_dpp v96, v8 row_ror:1 row_mask:0xf bank_mask:0xf
	v_mov_b32_dpp v97, v8 row_ror:2 row_mask:0xf bank_mask:0xf
	v_mov_b32_dpp v98, v9 row_ror:1 row_mask:0xf bank_mask:0xf
	v_mov_b32_dpp v99, v9 row_ror:2 row_mask:0xf bank_mask:0xf
	v_mov_b32_dpp v105, v10 row_ror:1 row_mask:0xf bank_mask:0xf
	v_mov_b32_dpp v106, v10 row_ror:2 row_mask:0xf bank_mask:0xf
	v_mov_b32_dpp v107, v11 row_ror:1 row_mask:0xf bank_mask:0xf
	v_mov_b32_dpp v108, v11 row_ror:2 row_mask:0xf bank_mask:0xf
	v_cndmask_b32_e64 v69, v71, v98, s[6:7]
	v_cndmask_b32_e64 v70, v102, v106, s[8:9]
	v_cndmask_b32_e64 v71, v104, v108, s[8:9]
	v_cndmask_b32_e64 v74, v73, v97, s[8:9]
	v_cndmask_b32_e64 v75, v100, v99, s[8:9]
	v_cndmask_b32_e64 v66, v101, v105, s[6:7]
	v_cndmask_b32_e64 v67, v103, v107, s[6:7]
	v_cndmask_b32_e64 v68, v65, v96, s[6:7]
	v_pk_fma_f32 v[70:71], v[86:87], v[70:71], v[82:83]
	v_pk_fma_f32 v[74:75], v[84:85], v[74:75], v[80:81]
	v_pk_fma_f32 v[66:67], v[90:91], v[66:67], v[70:71]
	v_pk_fma_f32 v[68:69], v[88:89], v[68:69], v[74:75]
	v_pk_fma_f32 v[10:11], v[10:11], v[94:95], v[66:67]
	v_pk_fma_f32 v[8:9], v[8:9], v[92:93], v[68:69]
	v_pk_mul_f32 v[6:7], v[6:7], v[64:65] op_sel_hi:[1,0]
	v_pk_mul_f32 v[4:5], v[4:5], v[64:65] op_sel_hi:[1,0]
	s_nop 1
	v_mov_b32_dpp v73, v4 row_ror:1 row_mask:0xf bank_mask:0xf
	v_mov_b32_dpp v74, v4 row_ror:2 row_mask:0xf bank_mask:0xf
	v_mov_b32_dpp v75, v5 row_ror:1 row_mask:0xf bank_mask:0xf
	v_mov_b32_dpp v100, v5 row_ror:2 row_mask:0xf bank_mask:0xf
	v_mov_b32_dpp v101, v6 row_ror:1 row_mask:0xf bank_mask:0xf
	v_mov_b32_dpp v102, v6 row_ror:2 row_mask:0xf bank_mask:0xf
	v_mov_b32_dpp v103, v7 row_ror:1 row_mask:0xf bank_mask:0xf
	v_mov_b32_dpp v104, v7 row_ror:2 row_mask:0xf bank_mask:0xf
	v_cndmask_b32_e64 v70, v97, v74, s[8:9]
	v_cndmask_b32_e64 v68, v106, v102, s[8:9]
	v_cndmask_b32_e64 v69, v108, v104, s[8:9]
	v_cndmask_b32_e64 v71, v99, v100, s[8:9]
	v_cndmask_b32_e64 v64, v105, v101, s[6:7]
	v_cndmask_b32_e64 v65, v107, v103, s[6:7]
	v_cndmask_b32_e64 v66, v96, v73, s[6:7]
	v_cndmask_b32_e64 v67, v98, v75, s[6:7]
	v_pk_fma_f32 v[68:69], v[86:87], v[68:69], v[82:83]
	v_pk_fma_f32 v[70:71], v[84:85], v[70:71], v[80:81]
	v_pk_fma_f32 v[64:65], v[90:91], v[64:65], v[68:69]
	v_pk_fma_f32 v[66:67], v[88:89], v[66:67], v[70:71]
	v_pk_fma_f32 v[6:7], v[6:7], v[94:95], v[64:65]
	v_pk_fma_f32 v[4:5], v[4:5], v[92:93], v[66:67]
	v_pk_mul_f32 v[2:3], v[2:3], v[72:73] op_sel_hi:[1,0]
	v_pk_mul_f32 v[0:1], v[0:1], v[72:73] op_sel_hi:[1,0]
	s_nop 1
	v_mov_b32_dpp v66, v0 row_ror:1 row_mask:0xf bank_mask:0xf
	v_mov_b32_dpp v70, v0 row_ror:2 row_mask:0xf bank_mask:0xf
	v_mov_b32_dpp v67, v1 row_ror:1 row_mask:0xf bank_mask:0xf
	v_mov_b32_dpp v71, v1 row_ror:2 row_mask:0xf bank_mask:0xf
	v_mov_b32_dpp v64, v2 row_ror:1 row_mask:0xf bank_mask:0xf
	v_mov_b32_dpp v68, v2 row_ror:2 row_mask:0xf bank_mask:0xf
	v_mov_b32_dpp v65, v3 row_ror:1 row_mask:0xf bank_mask:0xf
	v_mov_b32_dpp v69, v3 row_ror:2 row_mask:0xf bank_mask:0xf
	v_cndmask_b32_e64 v70, v74, v70, s[8:9]
	v_cndmask_b32_e64 v68, v102, v68, s[8:9]
	v_cndmask_b32_e64 v69, v104, v69, s[8:9]
	v_cndmask_b32_e64 v71, v100, v71, s[8:9]
	v_cndmask_b32_e64 v64, v101, v64, s[6:7]
	v_cndmask_b32_e64 v65, v103, v65, s[6:7]
	v_cndmask_b32_e64 v66, v73, v66, s[6:7]
	v_cndmask_b32_e64 v67, v75, v67, s[6:7]
	v_pk_fma_f32 v[68:69], v[86:87], v[68:69], v[82:83]
	v_pk_fma_f32 v[70:71], v[84:85], v[70:71], v[80:81]
	v_pk_fma_f32 v[64:65], v[90:91], v[64:65], v[68:69]
	v_pk_fma_f32 v[66:67], v[88:89], v[66:67], v[70:71]
	v_pk_fma_f32 v[2:3], v[2:3], v[94:95], v[64:65]
	v_pk_fma_f32 v[0:1], v[0:1], v[92:93], v[66:67]
	v_and_b32_e32 v67, 0x7fffffff, v61
	v_and_b32_e32 v66, 0x7fffffff, v60
	v_pk_fma_f32 v[66:67], v[66:67], s[58:59], 1.0 op_sel_hi:[1,0,0]
	v_pk_mul_f32 v[70:71], v[60:61], v[60:61]
	v_rcp_f32_e32 v66, v66
	v_rcp_f32_e32 v67, v67
	v_pk_mul_f32 v[70:71], v[70:71], s[50:51] op_sel_hi:[1,0]
	v_cmp_gt_f32_e32 vcc, 0, v60
	v_exp_f32_e32 v70, v70
	v_pk_fma_f32 v[68:69], v[66:67], s[60:61], v[128:129] op_sel_hi:[1,0,0]
	v_exp_f32_e32 v71, v71
	v_pk_fma_f32 v[68:69], v[66:67], v[68:69], s[62:63] op_sel_hi:[1,1,0]
	v_readlane_b32 s0, v244, 59
	v_pk_fma_f32 v[68:69], v[66:67], v[68:69], s[64:65] op_sel_hi:[1,1,0]
	s_nop 0
	v_pk_fma_f32 v[68:69], v[66:67], v[68:69], s[66:67] op_sel_hi:[1,1,0]
	v_add_u32_e32 v64, s0, v178
	v_pk_mul_f32 v[66:67], v[66:67], v[68:69]
	v_pk_mul_f32 v[68:69], v[62:63], v[62:63]
	v_pk_mul_f32 v[66:67], v[70:71], v[66:67]
	v_pk_mul_f32 v[68:69], v[68:69], s[50:51] op_sel_hi:[1,0]
	v_pk_mul_f32 v[70:71], v[60:61], v[66:67]
	v_pk_fma_f32 v[66:67], v[60:61], v[66:67], v[60:61] neg_lo:[1,0,0] neg_hi:[1,0,0]
	v_exp_f32_e32 v68, v68
	v_cndmask_b32_e32 v60, v66, v70, vcc
	v_cmp_gt_f32_e32 vcc, 0, v61
	v_and_b32_e32 v66, 0x7fffffff, v62
	v_exp_f32_e32 v69, v69
	v_cndmask_b32_e32 v61, v67, v71, vcc
	v_and_b32_e32 v67, 0x7fffffff, v63
	v_pk_fma_f32 v[66:67], v[66:67], s[58:59], 1.0 op_sel_hi:[1,0,0]
	v_cmp_gt_f32_e32 vcc, 0, v62
	v_rcp_f32_e32 v66, v66
	v_rcp_f32_e32 v67, v67
	v_pk_mul_f32 v[28:29], v[60:61], v[28:29]
	v_pk_fma_f32 v[70:71], v[66:67], s[60:61], v[128:129] op_sel_hi:[1,0,0]
; __device__ __forceinline__ u32x4 pack8(f32x4 v0, f32x4 v1) { u32x4 w; w.x = cvt_pk_bf16(v0[0], v0[1]); w.y = cvt_pk_bf16(v0[2], v0[3]); w.z = cvt_pk_bf16(v1[0], v1[1]); w.w = cvt_pk_bf16(v1[2], v1[3]); return w; }
; __device__ __forceinline__ f32x4 gelu4(f32x4 v) { f32x2 a = gelu_pk((f32x2){v[0], v[1]}), b = gelu_pk((f32x2){v[2], v[3]}); return (f32x4){a.x, a.y, b.x, b.y}; }
; __device__ __forceinline__ f32x2 gelu_pk(f32x2 v) {
;     const f32x2 av = __builtin_elementwise_abs(v), d = av * 0.2316418882f + 1.0f;
;     f32x2 t; t.x = __builtin_amdgcn_rcpf(d.x); t.y = __builtin_amdgcn_rcpf(d.y);
;     f32x2 q = t * 0.5307027145f + (-0.7265760135f); q = q * t + 0.7107068705f; q = q * t + (-0.142248368f); q = q * t + 0.127414796f; q = q * t;
;     const f32x2 s = (v * v) * (-0.72134752044f);
;     f32x2 e; e.x = __builtin_amdgcn_exp2f(s.x); e.y = __builtin_amdgcn_exp2f(s.y);
;     const f32x2 m = v * (q * e), r = v - m;
;     f32x2 o; o.x = v.x < 0.f ? m.x : r.x; o.y = v.y < 0.f ? m.y : r.y; return o;
;     __device__ __forceinline__ void operator()(f32x4 (&acc)[2][2][4][2], const Unit& u, int wr, int wc, int fr_, int fq_) const {
;     ...
;             for (int m = 0; m < 4; ++m) { const int row = u.pm * BM + blk * 64 + m * 16 + fr;
;                 const f32x4 g0 = gelu4(acc[ai][0][m][0]), g1 = gelu4(acc[ai][0][m][1]);
;                 *(u32x4*)(ACT + (size_t)row * 5632 + jcol) = pack8(g0 * acc[ai][1][m][0], g1 * acc[ai][1][m][1]); asm volatile("" ::: "memory"); __builtin_amdgcn_sched_barrier(0); }
	s_nop 0
	v_pk_fma_f32 v[70:71], v[66:67], v[70:71], s[62:63] op_sel_hi:[1,1,0]
	s_nop 0
	v_pk_fma_f32 v[70:71], v[66:67], v[70:71], s[64:65] op_sel_hi:[1,1,0]
	s_nop 0
	v_pk_fma_f32 v[70:71], v[66:67], v[70:71], s[66:67] op_sel_hi:[1,1,0]
	s_nop 0
	v_pk_mul_f32 v[66:67], v[66:67], v[70:71]
	v_pk_mul_f32 v[70:71], v[44:45], v[44:45]
	v_pk_mul_f32 v[66:67], v[68:69], v[66:67]
	v_pk_mul_f32 v[70:71], v[70:71], s[50:51] op_sel_hi:[1,0]
	v_pk_mul_f32 v[68:69], v[62:63], v[66:67]
	v_pk_fma_f32 v[66:67], v[62:63], v[66:67], v[62:63] neg_lo:[1,0,0] neg_hi:[1,0,0]
	v_exp_f32_e32 v70, v70
	v_cndmask_b32_e32 v62, v66, v68, vcc
	v_cmp_gt_f32_e32 vcc, 0, v63
	v_and_b32_e32 v66, 0x7fffffff, v44
	v_exp_f32_e32 v71, v71
	v_cndmask_b32_e32 v63, v67, v69, vcc
	v_and_b32_e32 v67, 0x7fffffff, v45
	v_pk_fma_f32 v[66:67], v[66:67], s[58:59], 1.0 op_sel_hi:[1,0,0]
	v_cmp_gt_f32_e32 vcc, 0, v44
	v_rcp_f32_e32 v66, v66
	v_rcp_f32_e32 v67, v67
	v_pk_mul_f32 v[30:31], v[62:63], v[30:31]
	v_pk_fma_f32 v[68:69], v[66:67], s[60:61], v[128:129] op_sel_hi:[1,0,0]
	s_nop 0
	v_pk_fma_f32 v[68:69], v[66:67], v[68:69], s[62:63] op_sel_hi:[1,1,0]
	s_nop 0
	v_pk_fma_f32 v[68:69], v[66:67], v[68:69], s[64:65] op_sel_hi:[1,1,0]
	s_nop 0
	v_pk_fma_f32 v[68:69], v[66:67], v[68:69], s[66:67] op_sel_hi:[1,1,0]
	s_nop 0
	v_pk_mul_f32 v[66:67], v[66:67], v[68:69]
	v_pk_mul_f32 v[68:69], v[46:47], v[46:47]
	v_pk_mul_f32 v[66:67], v[70:71], v[66:67]
	v_pk_mul_f32 v[68:69], v[68:69], s[50:51] op_sel_hi:[1,0]
	v_pk_mul_f32 v[70:71], v[44:45], v[66:67]
	v_pk_fma_f32 v[66:67], v[44:45], v[66:67], v[44:45] neg_lo:[1,0,0] neg_hi:[1,0,0]
	v_exp_f32_e32 v68, v68
	v_cndmask_b32_e32 v44, v66, v70, vcc
	v_cmp_gt_f32_e32 vcc, 0, v45
	v_and_b32_e32 v66, 0x7fffffff, v46
	v_exp_f32_e32 v69, v69
	v_cndmask_b32_e32 v45, v67, v71, vcc
	v_and_b32_e32 v67, 0x7fffffff, v47
	v_pk_fma_f32 v[66:67], v[66:67], s[58:59], 1.0 op_sel_hi:[1,0,0]
	v_cmp_gt_f32_e32 vcc, 0, v46
	v_rcp_f32_e32 v66, v66
	v_rcp_f32_e32 v67, v67
	s_nop 0
	v_pk_fma_f32 v[70:71], v[66:67], s[60:61], v[128:129] op_sel_hi:[1,0,0]
	s_nop 0
	v_pk_fma_f32 v[70:71], v[66:67], v[70:71], s[62:63] op_sel_hi:[1,1,0]
	s_nop 0
	v_pk_fma_f32 v[70:71], v[66:67], v[70:71], s[64:65] op_sel_hi:[1,1,0]
	s_nop 0
	v_pk_fma_f32 v[70:71], v[66:67], v[70:71], s[66:67] op_sel_hi:[1,1,0]
	s_nop 0
	v_pk_mul_f32 v[66:67], v[66:67], v[70:71]
	s_nop 0
	v_pk_mul_f32 v[66:67], v[68:69], v[66:67]
	s_nop 0
	v_pk_mul_f32 v[68:69], v[46:47], v[66:67]
	v_pk_fma_f32 v[66:67], v[46:47], v[66:67], v[46:47] neg_lo:[1,0,0] neg_hi:[1,0,0]
	s_nop 0
	v_cndmask_b32_e32 v46, v66, v68, vcc
	v_cmp_gt_f32_e32 vcc, 0, v47
	s_nop 1
	v_cndmask_b32_e32 v47, v67, v69, vcc
	v_pk_mul_f32 v[46:47], v[46:47], v[14:15]
	v_pk_mul_f32 v[14:15], v[44:45], v[12:13]
	v_cvt_pk_bf16_f32 v12, v28, v29
	v_mad_i64_i32 v[28:29], s[0:1], v64, s93, v[76:77]
	v_cvt_pk_bf16_f32 v13, v30, v31
	v_cvt_pk_bf16_f32 v14, v14, v15
	v_cvt_pk_bf16_f32 v15, v46, v47
	v_lshl_add_u64 v[28:29], v[28:29], 0, v[78:79]
	global_store_dwordx4 v[28:29], v[12:15], off
	s_nop 1
	v_and_b32_e32 v13, 0x7fffffff, v57
	v_and_b32_e32 v12, 0x7fffffff, v56
	v_pk_fma_f32 v[12:13], v[12:13], s[58:59], 1.0 op_sel_hi:[1,0,0]
	v_pk_mul_f32 v[28:29], v[56:57], v[56:57]
	v_rcp_f32_e32 v12, v12
	v_rcp_f32_e32 v13, v13
	v_pk_mul_f32 v[28:29], v[28:29], s[50:51] op_sel_hi:[1,0]
	v_cmp_gt_f32_e32 vcc, 0, v56
	v_exp_f32_e32 v28, v28
	v_pk_fma_f32 v[14:15], v[12:13], s[60:61], v[128:129] op_sel_hi:[1,0,0]
	v_exp_f32_e32 v29, v29
	v_pk_fma_f32 v[14:15], v[12:13], v[14:15], s[62:63] op_sel_hi:[1,1,0]
	v_pk_mul_f32 v[44:45], v[40:41], v[40:41]
	v_pk_fma_f32 v[14:15], v[12:13], v[14:15], s[64:65] op_sel_hi:[1,1,0]
	v_pk_mul_f32 v[44:45], v[44:45], s[50:51] op_sel_hi:[1,0]
	v_pk_fma_f32 v[14:15], v[12:13], v[14:15], s[66:67] op_sel_hi:[1,1,0]
	v_exp_f32_e32 v44, v44
	v_pk_mul_f32 v[12:13], v[12:13], v[14:15]
	v_pk_mul_f32 v[14:15], v[58:59], v[58:59]
	v_pk_mul_f32 v[12:13], v[28:29], v[12:13]
	v_pk_mul_f32 v[14:15], v[14:15], s[50:51] op_sel_hi:[1,0]
	v_pk_mul_f32 v[28:29], v[56:57], v[12:13]
	v_pk_fma_f32 v[12:13], v[56:57], v[12:13], v[56:57] neg_lo:[1,0,0] neg_hi:[1,0,0]
	v_exp_f32_e32 v14, v14
	v_cndmask_b32_e32 v12, v12, v28, vcc
	v_cmp_gt_f32_e32 vcc, 0, v57
	v_and_b32_e32 v28, 0x7fffffff, v58
	v_exp_f32_e32 v15, v15
	v_cndmask_b32_e32 v13, v13, v29, vcc
	v_and_b32_e32 v29, 0x7fffffff, v59
	v_pk_fma_f32 v[28:29], v[28:29], s[58:59], 1.0 op_sel_hi:[1,0,0]
	v_cmp_gt_f32_e32 vcc, 0, v58
	v_rcp_f32_e32 v28, v28
	v_rcp_f32_e32 v29, v29
	v_exp_f32_e32 v45, v45
	v_add_u32_e32 v46, 16, v64
	v_pk_mul_f32 v[12:13], v[12:13], v[24:25]
	v_pk_fma_f32 v[30:31], v[28:29], s[60:61], v[128:129] op_sel_hi:[1,0,0]
	s_nop 0
	v_pk_fma_f32 v[30:31], v[28:29], v[30:31], s[62:63] op_sel_hi:[1,1,0]
	s_nop 0
	v_pk_fma_f32 v[30:31], v[28:29], v[30:31], s[64:65] op_sel_hi:[1,1,0]
	s_nop 0
	v_pk_fma_f32 v[30:31], v[28:29], v[30:31], s[66:67] op_sel_hi:[1,1,0]
	s_nop 0
	v_pk_mul_f32 v[28:29], v[28:29], v[30:31]
	s_nop 0
	v_pk_mul_f32 v[14:15], v[14:15], v[28:29]
	s_nop 0
	v_pk_mul_f32 v[28:29], v[58:59], v[14:15]
	v_pk_fma_f32 v[14:15], v[58:59], v[14:15], v[58:59] neg_lo:[1,0,0] neg_hi:[1,0,0]
	s_nop 0
	v_cndmask_b32_e32 v14, v14, v28, vcc
	v_cmp_gt_f32_e32 vcc, 0, v59
	v_and_b32_e32 v28, 0x7fffffff, v40
	s_nop 0
	v_cndmask_b32_e32 v15, v15, v29, vcc
	v_and_b32_e32 v29, 0x7fffffff, v41
	v_pk_fma_f32 v[28:29], v[28:29], s[58:59], 1.0 op_sel_hi:[1,0,0]
	v_cmp_gt_f32_e32 vcc, 0, v40
	v_rcp_f32_e32 v28, v28
	v_rcp_f32_e32 v29, v29
	v_pk_mul_f32 v[14:15], v[14:15], v[26:27]
	v_pk_fma_f32 v[30:31], v[28:29], s[60:61], v[128:129] op_sel_hi:[1,0,0]
	s_nop 0
; __device__ __forceinline__ u32x4 pack8(f32x4 v0, f32x4 v1) { u32x4 w; w.x = cvt_pk_bf16(v0[0], v0[1]); w.y = cvt_pk_bf16(v0[2], v0[3]); w.z = cvt_pk_bf16(v1[0], v1[1]); w.w = cvt_pk_bf16(v1[2], v1[3]); return w; }
; __device__ __forceinline__ f32x4 gelu4(f32x4 v) { f32x2 a = gelu_pk((f32x2){v[0], v[1]}), b = gelu_pk((f32x2){v[2], v[3]}); return (f32x4){a.x, a.y, b.x, b.y}; }
; __device__ __forceinline__ f32x2 gelu_pk(f32x2 v) {
;     const f32x2 av = __builtin_elementwise_abs(v), d = av * 0.2316418882f + 1.0f;
;     f32x2 t; t.x = __builtin_amdgcn_rcpf(d.x); t.y = __builtin_amdgcn_rcpf(d.y);
;     f32x2 q = t * 0.5307027145f + (-0.7265760135f); q = q * t + 0.7107068705f; q = q * t + (-0.142248368f); q = q * t + 0.127414796f; q = q * t;
;     const f32x2 s = (v * v) * (-0.72134752044f);
;     f32x2 e; e.x = __builtin_amdgcn_exp2f(s.x); e.y = __builtin_amdgcn_exp2f(s.y);
;     const f32x2 m = v * (q * e), r = v - m;
;     f32x2 o; o.x = v.x < 0.f ? m.x : r.x; o.y = v.y < 0.f ? m.y : r.y; return o;
;     __device__ __forceinline__ void operator()(f32x4 (&acc)[2][2][4][2], const Unit& u, int wr, int wc, int fr_, int fq_) const {
;     ...
;             for (int m = 0; m < 4; ++m) { const int row = u.pm * BM + blk * 64 + m * 16 + fr;
;                 const f32x4 g0 = gelu4(acc[ai][0][m][0]), g1 = gelu4(acc[ai][0][m][1]);
;                 *(u32x4*)(ACT + (size_t)row * 5632 + jcol) = pack8(g0 * acc[ai][1][m][0], g1 * acc[ai][1][m][1]); asm volatile("" ::: "memory"); __builtin_amdgcn_sched_barrier(0); }
	v_pk_fma_f32 v[30:31], v[28:29], v[30:31], s[62:63] op_sel_hi:[1,1,0]
	s_nop 0
	v_pk_fma_f32 v[30:31], v[28:29], v[30:31], s[64:65] op_sel_hi:[1,1,0]
	s_nop 0
	v_pk_fma_f32 v[30:31], v[28:29], v[30:31], s[66:67] op_sel_hi:[1,1,0]
	s_nop 0
	v_pk_mul_f32 v[28:29], v[28:29], v[30:31]
	v_pk_mul_f32 v[30:31], v[42:43], v[42:43]
	v_pk_mul_f32 v[28:29], v[44:45], v[28:29]
	v_pk_mul_f32 v[30:31], v[30:31], s[50:51] op_sel_hi:[1,0]
	v_pk_mul_f32 v[44:45], v[40:41], v[28:29]
	v_pk_fma_f32 v[28:29], v[40:41], v[28:29], v[40:41] neg_lo:[1,0,0] neg_hi:[1,0,0]
	v_and_b32_e32 v40, 0x7fffffff, v42
	v_cndmask_b32_e32 v28, v28, v44, vcc
	v_cmp_gt_f32_e32 vcc, 0, v41
	v_and_b32_e32 v41, 0x7fffffff, v43
	v_pk_fma_f32 v[40:41], v[40:41], s[58:59], 1.0 op_sel_hi:[1,0,0]
	v_cndmask_b32_e32 v29, v29, v45, vcc
	v_rcp_f32_e32 v40, v40
	v_rcp_f32_e32 v41, v41
	v_exp_f32_e32 v30, v30
	v_exp_f32_e32 v31, v31
	v_cmp_gt_f32_e32 vcc, 0, v42
	v_pk_fma_f32 v[44:45], v[40:41], s[60:61], v[128:129] op_sel_hi:[1,0,0]
	s_nop 0
	v_pk_fma_f32 v[44:45], v[40:41], v[44:45], s[62:63] op_sel_hi:[1,1,0]
	s_nop 0
	v_pk_fma_f32 v[44:45], v[40:41], v[44:45], s[64:65] op_sel_hi:[1,1,0]
	s_nop 0
	v_pk_fma_f32 v[44:45], v[40:41], v[44:45], s[66:67] op_sel_hi:[1,1,0]
	s_nop 0
	v_pk_mul_f32 v[40:41], v[40:41], v[44:45]
	s_nop 0
	v_pk_mul_f32 v[30:31], v[30:31], v[40:41]
	s_nop 0
	v_pk_mul_f32 v[40:41], v[42:43], v[30:31]
	v_pk_fma_f32 v[30:31], v[42:43], v[30:31], v[42:43] neg_lo:[1,0,0] neg_hi:[1,0,0]
	s_nop 0
	v_cndmask_b32_e32 v30, v30, v40, vcc
	v_cmp_gt_f32_e32 vcc, 0, v43
	s_nop 1
	v_cndmask_b32_e32 v31, v31, v41, vcc
	v_pk_mul_f32 v[24:25], v[30:31], v[10:11]
	v_pk_mul_f32 v[10:11], v[28:29], v[8:9]
	v_cvt_pk_bf16_f32 v8, v12, v13
	v_mad_i64_i32 v[12:13], s[0:1], v46, s93, v[76:77]
	v_cvt_pk_bf16_f32 v9, v14, v15
	v_cvt_pk_bf16_f32 v10, v10, v11
	v_cvt_pk_bf16_f32 v11, v24, v25
	v_lshl_add_u64 v[12:13], v[12:13], 0, v[78:79]
	global_store_dwordx4 v[12:13], v[8:11], off
	s_nop 1
	v_and_b32_e32 v9, 0x7fffffff, v53
	v_and_b32_e32 v8, 0x7fffffff, v52
	v_pk_fma_f32 v[8:9], v[8:9], s[58:59], 1.0 op_sel_hi:[1,0,0]
	v_pk_mul_f32 v[12:13], v[52:53], v[52:53]
	v_rcp_f32_e32 v8, v8
	v_rcp_f32_e32 v9, v9
	v_pk_mul_f32 v[12:13], v[12:13], s[50:51] op_sel_hi:[1,0]
	v_cmp_gt_f32_e32 vcc, 0, v52
	v_exp_f32_e32 v12, v12
	v_pk_fma_f32 v[10:11], v[8:9], s[60:61], v[128:129] op_sel_hi:[1,0,0]
	v_exp_f32_e32 v13, v13
	v_pk_fma_f32 v[10:11], v[8:9], v[10:11], s[62:63] op_sel_hi:[1,1,0]
	v_pk_mul_f32 v[24:25], v[36:37], v[36:37]
	v_pk_fma_f32 v[10:11], v[8:9], v[10:11], s[64:65] op_sel_hi:[1,1,0]
	v_pk_mul_f32 v[24:25], v[24:25], s[50:51] op_sel_hi:[1,0]
	v_pk_fma_f32 v[10:11], v[8:9], v[10:11], s[66:67] op_sel_hi:[1,1,0]
	v_exp_f32_e32 v24, v24
	v_pk_mul_f32 v[8:9], v[8:9], v[10:11]
	v_pk_mul_f32 v[10:11], v[54:55], v[54:55]
	v_pk_mul_f32 v[8:9], v[12:13], v[8:9]
	v_pk_mul_f32 v[10:11], v[10:11], s[50:51] op_sel_hi:[1,0]
	v_pk_mul_f32 v[12:13], v[52:53], v[8:9]
	v_pk_fma_f32 v[8:9], v[52:53], v[8:9], v[52:53] neg_lo:[1,0,0] neg_hi:[1,0,0]
	v_exp_f32_e32 v10, v10
	v_cndmask_b32_e32 v8, v8, v12, vcc
	v_cmp_gt_f32_e32 vcc, 0, v53
	v_and_b32_e32 v12, 0x7fffffff, v54
	v_exp_f32_e32 v11, v11
	v_cndmask_b32_e32 v9, v9, v13, vcc
	v_and_b32_e32 v13, 0x7fffffff, v55
	v_pk_fma_f32 v[12:13], v[12:13], s[58:59], 1.0 op_sel_hi:[1,0,0]
	v_cmp_gt_f32_e32 vcc, 0, v54
	v_rcp_f32_e32 v12, v12
	v_rcp_f32_e32 v13, v13
	v_exp_f32_e32 v25, v25
	v_add_u32_e32 v28, 32, v64
	v_pk_mul_f32 v[8:9], v[8:9], v[20:21]
	v_pk_fma_f32 v[14:15], v[12:13], s[60:61], v[128:129] op_sel_hi:[1,0,0]
	s_nop 0
	v_pk_fma_f32 v[14:15], v[12:13], v[14:15], s[62:63] op_sel_hi:[1,1,0]
	s_nop 0
	v_pk_fma_f32 v[14:15], v[12:13], v[14:15], s[64:65] op_sel_hi:[1,1,0]
	s_nop 0
	v_pk_fma_f32 v[14:15], v[12:13], v[14:15], s[66:67] op_sel_hi:[1,1,0]
	s_nop 0
	v_pk_mul_f32 v[12:13], v[12:13], v[14:15]
	s_nop 0
	v_pk_mul_f32 v[10:11], v[10:11], v[12:13]
	s_nop 0
	v_pk_mul_f32 v[12:13], v[54:55], v[10:11]
	v_pk_fma_f32 v[10:11], v[54:55], v[10:11], v[54:55] neg_lo:[1,0,0] neg_hi:[1,0,0]
	s_nop 0
	v_cndmask_b32_e32 v10, v10, v12, vcc
	v_cmp_gt_f32_e32 vcc, 0, v55
	v_and_b32_e32 v12, 0x7fffffff, v36
	s_nop 0
	v_cndmask_b32_e32 v11, v11, v13, vcc
	v_and_b32_e32 v13, 0x7fffffff, v37
	v_pk_fma_f32 v[12:13], v[12:13], s[58:59], 1.0 op_sel_hi:[1,0,0]
	v_cmp_gt_f32_e32 vcc, 0, v36
	v_rcp_f32_e32 v12, v12
	v_rcp_f32_e32 v13, v13
	v_pk_mul_f32 v[10:11], v[10:11], v[22:23]
	v_pk_fma_f32 v[14:15], v[12:13], s[60:61], v[128:129] op_sel_hi:[1,0,0]
	s_nop 0
	v_pk_fma_f32 v[14:15], v[12:13], v[14:15], s[62:63] op_sel_hi:[1,1,0]
	s_nop 0
	v_pk_fma_f32 v[14:15], v[12:13], v[14:15], s[64:65] op_sel_hi:[1,1,0]
	s_nop 0
	v_pk_fma_f32 v[14:15], v[12:13], v[14:15], s[66:67] op_sel_hi:[1,1,0]
	s_nop 0
	v_pk_mul_f32 v[12:13], v[12:13], v[14:15]
	v_pk_mul_f32 v[14:15], v[38:39], v[38:39]
	v_pk_mul_f32 v[12:13], v[24:25], v[12:13]
	v_pk_mul_f32 v[14:15], v[14:15], s[50:51] op_sel_hi:[1,0]
	v_pk_mul_f32 v[24:25], v[36:37], v[12:13]
	v_pk_fma_f32 v[12:13], v[36:37], v[12:13], v[36:37] neg_lo:[1,0,0] neg_hi:[1,0,0]
	v_exp_f32_e32 v14, v14
	v_cndmask_b32_e32 v12, v12, v24, vcc
	v_cmp_gt_f32_e32 vcc, 0, v37
	v_and_b32_e32 v24, 0x7fffffff, v38
	v_exp_f32_e32 v15, v15
	v_cndmask_b32_e32 v13, v13, v25, vcc
	v_and_b32_e32 v25, 0x7fffffff, v39
	v_pk_fma_f32 v[24:25], v[24:25], s[58:59], 1.0 op_sel_hi:[1,0,0]
	v_cmp_gt_f32_e32 vcc, 0, v38
	v_rcp_f32_e32 v24, v24
	v_rcp_f32_e32 v25, v25
	s_nop 0
	v_pk_fma_f32 v[26:27], v[24:25], s[60:61], v[128:129] op_sel_hi:[1,0,0]
; __device__ __forceinline__ u32x4 pack8(f32x4 v0, f32x4 v1) { u32x4 w; w.x = cvt_pk_bf16(v0[0], v0[1]); w.y = cvt_pk_bf16(v0[2], v0[3]); w.z = cvt_pk_bf16(v1[0], v1[1]); w.w = cvt_pk_bf16(v1[2], v1[3]); return w; }
; __device__ __forceinline__ f32x4 gelu4(f32x4 v) { f32x2 a = gelu_pk((f32x2){v[0], v[1]}), b = gelu_pk((f32x2){v[2], v[3]}); return (f32x4){a.x, a.y, b.x, b.y}; }
; __device__ __forceinline__ f32x2 gelu_pk(f32x2 v) {
;     const f32x2 av = __builtin_elementwise_abs(v), d = av * 0.2316418882f + 1.0f;
;     f32x2 t; t.x = __builtin_amdgcn_rcpf(d.x); t.y = __builtin_amdgcn_rcpf(d.y);
;     f32x2 q = t * 0.5307027145f + (-0.7265760135f); q = q * t + 0.7107068705f; q = q * t + (-0.142248368f); q = q * t + 0.127414796f; q = q * t;
;     const f32x2 s = (v * v) * (-0.72134752044f);
;     f32x2 e; e.x = __builtin_amdgcn_exp2f(s.x); e.y = __builtin_amdgcn_exp2f(s.y);
;     const f32x2 m = v * (q * e), r = v - m;
;     f32x2 o; o.x = v.x < 0.f ? m.x : r.x; o.y = v.y < 0.f ? m.y : r.y; return o;
;     __device__ __forceinline__ void operator()(f32x4 (&acc)[2][2][4][2], const Unit& u, int wr, int wc, int fr_, int fq_) const {
;     ...
;             for (int m = 0; m < 4; ++m) { const int row = u.pm * BM + blk * 64 + m * 16 + fr;
;                 const f32x4 g0 = gelu4(acc[ai][0][m][0]), g1 = gelu4(acc[ai][0][m][1]);
;                 *(u32x4*)(ACT + (size_t)row * 5632 + jcol) = pack8(g0 * acc[ai][1][m][0], g1 * acc[ai][1][m][1]); asm volatile("" ::: "memory"); __builtin_amdgcn_sched_barrier(0); }
	s_nop 0
	v_pk_fma_f32 v[26:27], v[24:25], v[26:27], s[62:63] op_sel_hi:[1,1,0]
	s_nop 0
	v_pk_fma_f32 v[26:27], v[24:25], v[26:27], s[64:65] op_sel_hi:[1,1,0]
	s_nop 0
	v_pk_fma_f32 v[26:27], v[24:25], v[26:27], s[66:67] op_sel_hi:[1,1,0]
	s_nop 0
	v_pk_mul_f32 v[24:25], v[24:25], v[26:27]
	s_nop 0
	v_pk_mul_f32 v[14:15], v[14:15], v[24:25]
	s_nop 0
	v_pk_mul_f32 v[24:25], v[38:39], v[14:15]
	v_pk_fma_f32 v[14:15], v[38:39], v[14:15], v[38:39] neg_lo:[1,0,0] neg_hi:[1,0,0]
	s_nop 0
	v_cndmask_b32_e32 v14, v14, v24, vcc
	v_cmp_gt_f32_e32 vcc, 0, v39
	s_nop 1
	v_cndmask_b32_e32 v15, v15, v25, vcc
	v_pk_mul_f32 v[14:15], v[14:15], v[6:7]
	v_pk_mul_f32 v[6:7], v[12:13], v[4:5]
	v_cvt_pk_bf16_f32 v4, v8, v9
	v_mad_i64_i32 v[8:9], s[0:1], v28, s93, v[76:77]
	v_cvt_pk_bf16_f32 v5, v10, v11
	v_cvt_pk_bf16_f32 v6, v6, v7
	v_cvt_pk_bf16_f32 v7, v14, v15
	v_lshl_add_u64 v[8:9], v[8:9], 0, v[78:79]
	global_store_dwordx4 v[8:9], v[4:7], off
	s_nop 1
	v_and_b32_e32 v5, 0x7fffffff, v49
	v_and_b32_e32 v4, 0x7fffffff, v48
	v_pk_fma_f32 v[4:5], v[4:5], s[58:59], 1.0 op_sel_hi:[1,0,0]
	v_pk_mul_f32 v[8:9], v[48:49], v[48:49]
	v_rcp_f32_e32 v4, v4
	v_rcp_f32_e32 v5, v5
	v_pk_mul_f32 v[8:9], v[8:9], s[50:51] op_sel_hi:[1,0]
	v_cmp_gt_f32_e32 vcc, 0, v48
	v_exp_f32_e32 v8, v8
	v_pk_fma_f32 v[6:7], v[4:5], s[60:61], v[128:129] op_sel_hi:[1,0,0]
	v_exp_f32_e32 v9, v9
	v_pk_fma_f32 v[6:7], v[4:5], v[6:7], s[62:63] op_sel_hi:[1,1,0]
	v_pk_mul_f32 v[12:13], v[32:33], v[32:33]
	v_pk_fma_f32 v[6:7], v[4:5], v[6:7], s[64:65] op_sel_hi:[1,1,0]
	v_pk_mul_f32 v[12:13], v[12:13], s[50:51] op_sel_hi:[1,0]
	v_pk_fma_f32 v[6:7], v[4:5], v[6:7], s[66:67] op_sel_hi:[1,1,0]
	v_exp_f32_e32 v12, v12
	v_pk_mul_f32 v[4:5], v[4:5], v[6:7]
	v_pk_mul_f32 v[6:7], v[50:51], v[50:51]
	v_pk_mul_f32 v[4:5], v[8:9], v[4:5]
	v_pk_mul_f32 v[6:7], v[6:7], s[50:51] op_sel_hi:[1,0]
	v_pk_mul_f32 v[8:9], v[48:49], v[4:5]
	v_pk_fma_f32 v[4:5], v[48:49], v[4:5], v[48:49] neg_lo:[1,0,0] neg_hi:[1,0,0]
	v_exp_f32_e32 v6, v6
	v_cndmask_b32_e32 v4, v4, v8, vcc
	v_cmp_gt_f32_e32 vcc, 0, v49
	v_and_b32_e32 v8, 0x7fffffff, v50
	v_exp_f32_e32 v7, v7
	v_cndmask_b32_e32 v5, v5, v9, vcc
	v_and_b32_e32 v9, 0x7fffffff, v51
	v_pk_fma_f32 v[8:9], v[8:9], s[58:59], 1.0 op_sel_hi:[1,0,0]
	v_cmp_gt_f32_e32 vcc, 0, v50
	v_rcp_f32_e32 v8, v8
	v_rcp_f32_e32 v9, v9
	v_exp_f32_e32 v13, v13
	v_add_u32_e32 v20, 48, v64
	v_pk_mul_f32 v[4:5], v[4:5], v[16:17]
	v_pk_fma_f32 v[10:11], v[8:9], s[60:61], v[128:129] op_sel_hi:[1,0,0]
	s_nop 0
	v_pk_fma_f32 v[10:11], v[8:9], v[10:11], s[62:63] op_sel_hi:[1,1,0]
	s_nop 0
	v_pk_fma_f32 v[10:11], v[8:9], v[10:11], s[64:65] op_sel_hi:[1,1,0]
	s_nop 0
	v_pk_fma_f32 v[10:11], v[8:9], v[10:11], s[66:67] op_sel_hi:[1,1,0]
	s_nop 0
	v_pk_mul_f32 v[8:9], v[8:9], v[10:11]
	s_nop 0
	v_pk_mul_f32 v[6:7], v[6:7], v[8:9]
	s_nop 0
	v_pk_mul_f32 v[8:9], v[50:51], v[6:7]
	v_pk_fma_f32 v[6:7], v[50:51], v[6:7], v[50:51] neg_lo:[1,0,0] neg_hi:[1,0,0]
	s_nop 0
	v_cndmask_b32_e32 v6, v6, v8, vcc
	v_cmp_gt_f32_e32 vcc, 0, v51
	v_and_b32_e32 v8, 0x7fffffff, v32
	s_nop 0
	v_cndmask_b32_e32 v7, v7, v9, vcc
	v_and_b32_e32 v9, 0x7fffffff, v33
	v_pk_fma_f32 v[8:9], v[8:9], s[58:59], 1.0 op_sel_hi:[1,0,0]
	v_cmp_gt_f32_e32 vcc, 0, v32
	v_rcp_f32_e32 v8, v8
	v_rcp_f32_e32 v9, v9
	v_pk_mul_f32 v[6:7], v[6:7], v[18:19]
	v_pk_fma_f32 v[10:11], v[8:9], s[60:61], v[128:129] op_sel_hi:[1,0,0]
	s_nop 0
	v_pk_fma_f32 v[10:11], v[8:9], v[10:11], s[62:63] op_sel_hi:[1,1,0]
	s_nop 0
	v_pk_fma_f32 v[10:11], v[8:9], v[10:11], s[64:65] op_sel_hi:[1,1,0]
	s_nop 0
	v_pk_fma_f32 v[10:11], v[8:9], v[10:11], s[66:67] op_sel_hi:[1,1,0]
	s_nop 0
	v_pk_mul_f32 v[8:9], v[8:9], v[10:11]
	v_pk_mul_f32 v[10:11], v[34:35], v[34:35]
	v_pk_mul_f32 v[8:9], v[12:13], v[8:9]
	v_pk_mul_f32 v[10:11], v[10:11], s[50:51] op_sel_hi:[1,0]
	v_pk_mul_f32 v[12:13], v[32:33], v[8:9]
	v_pk_fma_f32 v[8:9], v[32:33], v[8:9], v[32:33] neg_lo:[1,0,0] neg_hi:[1,0,0]
	v_exp_f32_e32 v10, v10
	v_cndmask_b32_e32 v8, v8, v12, vcc
	v_cmp_gt_f32_e32 vcc, 0, v33
	v_and_b32_e32 v12, 0x7fffffff, v34
	v_exp_f32_e32 v11, v11
	v_cndmask_b32_e32 v9, v9, v13, vcc
	v_and_b32_e32 v13, 0x7fffffff, v35
	v_pk_fma_f32 v[12:13], v[12:13], s[58:59], 1.0 op_sel_hi:[1,0,0]
	v_cmp_gt_f32_e32 vcc, 0, v34
	v_rcp_f32_e32 v12, v12
	v_rcp_f32_e32 v13, v13
	s_nop 0
	v_pk_fma_f32 v[14:15], v[12:13], s[60:61], v[128:129] op_sel_hi:[1,0,0]
	s_nop 0
	v_pk_fma_f32 v[14:15], v[12:13], v[14:15], s[62:63] op_sel_hi:[1,1,0]
	s_nop 0
	v_pk_fma_f32 v[14:15], v[12:13], v[14:15], s[64:65] op_sel_hi:[1,1,0]
	s_nop 0
	v_pk_fma_f32 v[14:15], v[12:13], v[14:15], s[66:67] op_sel_hi:[1,1,0]
	s_nop 0
	v_pk_mul_f32 v[12:13], v[12:13], v[14:15]
	s_nop 0
	v_pk_mul_f32 v[10:11], v[10:11], v[12:13]
	s_nop 0
	v_pk_mul_f32 v[12:13], v[34:35], v[10:11]
	v_pk_fma_f32 v[10:11], v[34:35], v[10:11], v[34:35] neg_lo:[1,0,0] neg_hi:[1,0,0]
	s_nop 0
	v_cndmask_b32_e32 v10, v10, v12, vcc
	v_cmp_gt_f32_e32 vcc, 0, v35
	s_nop 1
	v_cndmask_b32_e32 v11, v11, v13, vcc
	v_pk_mul_f32 v[10:11], v[10:11], v[2:3]
	v_pk_mul_f32 v[2:3], v[8:9], v[0:1]
	v_cvt_pk_bf16_f32 v0, v4, v5
	v_mad_i64_i32 v[4:5], s[0:1], v20, s93, v[76:77]
	v_cvt_pk_bf16_f32 v1, v6, v7
	v_cvt_pk_bf16_f32 v2, v2, v3
	v_cvt_pk_bf16_f32 v3, v10, v11
	v_lshl_add_u64 v[4:5], v[4:5], 0, v[78:79]
	global_store_dwordx4 v[4:5], v[0:3], off
	s_andn2_b64 vcc, exec, s[4:5]
	s_mov_b64 s[0:1], -1
	s_cbranch_vccnz .LBB0_1697
	s_andn2_b64 vcc, exec, s[18:19]
	s_cbranch_vccnz .LBB0_1696
	s_barrier
	s_branch .LBB0_1696
